# FFN-up GEMMs: half-workgroup epilogues run one after the other (no extra pairing barrier), each beside the other half's MFMA block
# baseline (speedup 1.0000x reference)
; #define PG8_STAGE(bufoff, gbase, voff) do { _Pragma("unroll") for (int _i = 0; _i < 2; ++_i) \
;         __builtin_amdgcn_global_load_lds((const unsigned*)((const char*)(gbase) + (voff)[_i]), (PG8_LAS unsigned*)(lds + (bufoff) + ldsw + _i * 8192), 16, 0, 0); } while (0)
; #define PG8_LDA(dst, b, h) do { _Pragma("unroll") for (int m = 0; m < 4; ++m) _Pragma("unroll") for (int k = 0; k < 2; ++k) dst[m][k] = *(const PG8_LAS bf16x8*)(lds + PG8_SA(b, h) + aoff + m * 2048 + k * 1024); } while (0)
; #define PG8_LDB(dst, b, h) do { _Pragma("unroll") for (int n = 0; n < 2; ++n) _Pragma("unroll") for (int k = 0; k < 2; ++k) dst[n][k] = *(const PG8_LAS bf16x8*)(lds + PG8_SB(b, h) + boff + n * 2048 + k * 1024); } while (0)
; #define PG8_MMA(ai, bj, At, Bt) do { __builtin_amdgcn_s_setprio(1); _Pragma("unroll") for (int m = 0; m < 4; ++m) _Pragma("unroll") for (int n = 0; n < 2; ++n) _Pragma("unroll") for (int k = 0; k < 2; ++k) \
;         acc[ai][bj][m][n] = __builtin_amdgcn_mfma_f32_16x16x32_bf16(Bt[n][k], At[m][k], acc[ai][bj][m][n], 0, 0, 0); __builtin_amdgcn_s_setprio(0); } while (0)
; #define PG8_WAIT_V(n) asm volatile("s_waitcnt vmcnt(" #n ")" ::: "memory")
; #define PG8_WAIT_L(n) asm volatile("s_waitcnt lgkmcnt(" #n ")" ::: "memory")
; #define PG8_BAR __builtin_amdgcn_s_barrier()
; #define PG8_SCHED __builtin_amdgcn_sched_barrier(0)
; template <class Epi, class Sched, bool ALIGN_EPI = false, bool SP2 = false>
; __device__ __forceinline__ void gemm_phase(PG8_LAS unsigned char* lds, const Gemm g, const Sched& S, const Epi& E) {
;     ...
;             PG8_LDB(B0, 0, 0); PG8_LDB(B1, 0, 1); PG8_SCHED; PG8_LDA(At, 0, 0); PG8_STAGE(PG8_SA(1, 1), a1 + hstep, voffA);
;             PG8_WAIT_V(8); PG8_WAIT_L(0); PG8_BAR; PG8_MMA(0, 0, At, B0); PG8_MMA(0, 1, At, B1); PG8_BAR; PG8_SCHED;
;             PG8_LDA(At, 0, 1); PG8_STAGE(PG8_SB(0, 0), b2, voffB); PG8_STAGE(PG8_SB(0, 1), b2 + hstep, voffB); PG8_STAGE(PG8_SA(0, 0), a2, voffA);
;             PG8_WAIT_V(8); PG8_WAIT_L(0); PG8_BAR; PG8_MMA(1, 0, At, B0); PG8_MMA(1, 1, At, B1); PG8_BAR; PG8_SCHED;
.LBB0_192:
	ds_read_b128 v[152:155], v149
	ds_read_b128 v[156:159], v149 offset:1024
	ds_read_b128 v[160:163], v149 offset:2048
	ds_read_b128 v[164:167], v149 offset:3072
	ds_read_b128 v[168:171], v150
	ds_read_b128 v[172:175], v150 offset:1024
	ds_read_b128 v[176:179], v150 offset:2048
	ds_read_b128 v[182:185], v150 offset:3072
	s_add_u32 s44, s42, 0xfffc0080
	s_addc_u32 s45, s43, -1
	s_cmp_eq_u32 s92, 12
	s_cselect_b32 s47, s23, s45
	s_cselect_b32 s46, s88, s44
	s_cselect_b32 s45, s21, s91
	s_cselect_b32 s44, s89, s90
	v_lshl_add_u64 v[144:145], s[42:43], 0, v[136:137]
	s_add_i32 m0, s41, 0xc000
	ds_read_b128 v[186:189], v151
	ds_read_b128 v[192:195], v151 offset:1024
	ds_read_b128 v[196:199], v151 offset:2048
	ds_read_b128 v[200:203], v151 offset:3072
	ds_read_b128 v[204:207], v151 offset:4096
	ds_read_b128 v[208:211], v151 offset:5120
	ds_read_b128 v[212:215], v151 offset:6144
	ds_read_b128 v[216:219], v151 offset:7168
	global_load_lds_dwordx4 v[144:145], off
	v_lshl_add_u64 v[144:145], s[42:43], 0, v[138:139]
	s_add_i32 m0, s41, 0xe000
	s_nop 0
	global_load_lds_dwordx4 v[144:145], off
	s_waitcnt vmcnt(8)
	s_waitcnt lgkmcnt(0)
	s_barrier
	s_setprio 1
	s_waitcnt lgkmcnt(0)
	v_mfma_f32_16x16x32_bf16 v[124:127], v[152:155], v[186:189], v[124:127]
	v_mfma_f32_16x16x32_bf16 v[116:119], v[160:163], v[186:189], v[116:119]
	v_mfma_f32_16x16x32_bf16 v[108:111], v[152:155], v[196:199], v[108:111]
	v_mfma_f32_16x16x32_bf16 v[100:103], v[160:163], v[196:199], v[100:103]
	v_mfma_f32_16x16x32_bf16 v[92:95], v[152:155], v[204:207], v[92:95]
	v_mfma_f32_16x16x32_bf16 v[84:87], v[160:163], v[204:207], v[84:87]
	v_mfma_f32_16x16x32_bf16 v[76:79], v[152:155], v[212:215], v[76:79]
	v_mfma_f32_16x16x32_bf16 v[68:71], v[160:163], v[212:215], v[68:71]
	v_mfma_f32_16x16x32_bf16 v[124:127], v[156:159], v[192:195], v[124:127]
	v_mfma_f32_16x16x32_bf16 v[116:119], v[164:167], v[192:195], v[116:119]
	v_mfma_f32_16x16x32_bf16 v[108:111], v[156:159], v[200:203], v[108:111]
	v_mfma_f32_16x16x32_bf16 v[100:103], v[164:167], v[200:203], v[100:103]
	v_mfma_f32_16x16x32_bf16 v[92:95], v[156:159], v[208:211], v[92:95]
	v_mfma_f32_16x16x32_bf16 v[84:87], v[164:167], v[208:211], v[84:87]
	v_mfma_f32_16x16x32_bf16 v[76:79], v[156:159], v[216:219], v[76:79]
	v_mfma_f32_16x16x32_bf16 v[68:71], v[164:167], v[216:219], v[68:71]
	s_setprio 0
	s_setprio 1
	v_mfma_f32_16x16x32_bf16 v[120:123], v[168:171], v[186:189], v[120:123]
	v_mfma_f32_16x16x32_bf16 v[112:115], v[176:179], v[186:189], v[112:115]
	v_mfma_f32_16x16x32_bf16 v[104:107], v[168:171], v[196:199], v[104:107]
	v_mfma_f32_16x16x32_bf16 v[96:99], v[176:179], v[196:199], v[96:99]
	v_mfma_f32_16x16x32_bf16 v[88:91], v[168:171], v[204:207], v[88:91]
	v_mfma_f32_16x16x32_bf16 v[80:83], v[176:179], v[204:207], v[80:83]
	v_mfma_f32_16x16x32_bf16 v[72:75], v[168:171], v[212:215], v[72:75]
	v_mfma_f32_16x16x32_bf16 v[64:67], v[176:179], v[212:215], v[64:67]
	v_mfma_f32_16x16x32_bf16 v[120:123], v[172:175], v[192:195], v[120:123]
	v_mfma_f32_16x16x32_bf16 v[112:115], v[182:185], v[192:195], v[112:115]
	v_mfma_f32_16x16x32_bf16 v[104:107], v[172:175], v[200:203], v[104:107]
	v_mfma_f32_16x16x32_bf16 v[96:99], v[182:185], v[200:203], v[96:99]
	v_mfma_f32_16x16x32_bf16 v[88:91], v[172:175], v[208:211], v[88:91]
	v_mfma_f32_16x16x32_bf16 v[80:83], v[182:185], v[208:211], v[80:83]
	v_mfma_f32_16x16x32_bf16 v[72:75], v[172:175], v[216:219], v[72:75]
	v_mfma_f32_16x16x32_bf16 v[64:67], v[182:185], v[216:219], v[64:67]
	s_setprio 0
	s_barrier
	s_add_i32 s93, s84, s48
	v_lshl_add_u64 v[144:145], s[44:45], 0, v[132:133]
	s_mov_b32 m0, s93
	ds_read_b128 v[186:189], v151 offset:16384
	ds_read_b128 v[192:195], v151 offset:17408
	ds_read_b128 v[196:199], v151 offset:18432
	ds_read_b128 v[200:203], v151 offset:19456
	ds_read_b128 v[204:207], v151 offset:20480
	ds_read_b128 v[208:211], v151 offset:21504
	ds_read_b128 v[212:215], v151 offset:22528
	ds_read_b128 v[216:219], v151 offset:23552
	global_load_lds_dwordx4 v[144:145], off
	s_add_i32 m0, s93, 0x2000
	s_add_u32 s94, s44, 0x40000
	v_lshl_add_u64 v[220:221], s[44:45], 0, v[128:129]
	s_addc_u32 s95, s45, 0
	s_add_i32 s93, s85, s48
	global_load_lds_dwordx4 v[220:221], off
	v_lshl_add_u64 v[222:223], s[94:95], 0, v[132:133]
	s_mov_b32 m0, s93
	v_lshl_add_u64 v[224:225], s[46:47], 0, v[130:131]
	global_load_lds_dwordx4 v[222:223], off
	v_lshl_add_u64 v[222:223], s[94:95], 0, v[128:129]
	s_add_i32 m0, s93, 0x2000
	s_nop 0
	global_load_lds_dwordx4 v[222:223], off
	v_lshl_add_u64 v[222:223], s[46:47], 0, v[134:135]
	s_mov_b32 m0, s41
	s_nop 0
	global_load_lds_dwordx4 v[222:223], off
	s_mov_b32 m0, s61
	s_nop 0
	global_load_lds_dwordx4 v[224:225], off
	s_waitcnt vmcnt(8)
	s_waitcnt lgkmcnt(0)
	s_barrier
; #define PG8_STAGE(bufoff, gbase, voff) do { _Pragma("unroll") for (int _i = 0; _i < 2; ++_i) \
;         __builtin_amdgcn_global_load_lds((const unsigned*)((const char*)(gbase) + (voff)[_i]), (PG8_LAS unsigned*)(lds + (bufoff) + ldsw + _i * 8192), 16, 0, 0); } while (0)
; #define PG8_LDA(dst, b, h) do { _Pragma("unroll") for (int m = 0; m < 4; ++m) _Pragma("unroll") for (int k = 0; k < 2; ++k) dst[m][k] = *(const PG8_LAS bf16x8*)(lds + PG8_SA(b, h) + aoff + m * 2048 + k * 1024); } while (0)
; #define PG8_LDB(dst, b, h) do { _Pragma("unroll") for (int n = 0; n < 2; ++n) _Pragma("unroll") for (int k = 0; k < 2; ++k) dst[n][k] = *(const PG8_LAS bf16x8*)(lds + PG8_SB(b, h) + boff + n * 2048 + k * 1024); } while (0)
; #define PG8_MMA(ai, bj, At, Bt) do { __builtin_amdgcn_s_setprio(1); _Pragma("unroll") for (int m = 0; m < 4; ++m) _Pragma("unroll") for (int n = 0; n < 2; ++n) _Pragma("unroll") for (int k = 0; k < 2; ++k) \
;         acc[ai][bj][m][n] = __builtin_amdgcn_mfma_f32_16x16x32_bf16(Bt[n][k], At[m][k], acc[ai][bj][m][n], 0, 0, 0); __builtin_amdgcn_s_setprio(0); } while (0)
; #define PG8_WAIT_V(n) asm volatile("s_waitcnt vmcnt(" #n ")" ::: "memory")
; #define PG8_WAIT_L(n) asm volatile("s_waitcnt lgkmcnt(" #n ")" ::: "memory")
; #define PG8_BAR __builtin_amdgcn_s_barrier()
; #define PG8_SCHED __builtin_amdgcn_sched_barrier(0)
; template <class Epi, class Sched, bool ALIGN_EPI = false, bool SP2 = false>
; __device__ __forceinline__ void gemm_phase(PG8_LAS unsigned char* lds, const Gemm g, const Sched& S, const Epi& E) {
;     ...
;             PG8_WAIT_V(8); PG8_WAIT_L(0); PG8_BAR; PG8_MMA(1, 0, At, B0); PG8_MMA(1, 1, At, B1); PG8_BAR; PG8_SCHED;
;             PG8_LDB(B0, 1, 0); PG8_LDB(B1, 1, 1); PG8_SCHED; PG8_LDA(At, 1, 0); PG8_STAGE(PG8_SA(0, 1), a2 + hstep, voffA);
;             PG8_WAIT_V(8); PG8_WAIT_L(0); PG8_BAR; PG8_MMA(0, 0, At, B0); PG8_MMA(0, 1, At, B1); PG8_BAR; PG8_SCHED;
;             PG8_LDA(At, 1, 1); PG8_STAGE(PG8_SB(1, 0), b3, voffB); PG8_STAGE(PG8_SB(1, 1), b3 + hstep, voffB); PG8_STAGE(PG8_SA(1, 0), a3, voffA);
	s_setprio 1
	s_waitcnt lgkmcnt(0)
	v_mfma_f32_16x16x32_bf16 v[60:63], v[152:155], v[186:189], v[60:63]
	v_mfma_f32_16x16x32_bf16 v[52:55], v[160:163], v[186:189], v[52:55]
	v_mfma_f32_16x16x32_bf16 v[44:47], v[152:155], v[196:199], v[44:47]
	v_mfma_f32_16x16x32_bf16 v[36:39], v[160:163], v[196:199], v[36:39]
	v_mfma_f32_16x16x32_bf16 v[28:31], v[152:155], v[204:207], v[28:31]
	v_mfma_f32_16x16x32_bf16 v[20:23], v[160:163], v[204:207], v[20:23]
	v_mfma_f32_16x16x32_bf16 v[12:15], v[152:155], v[212:215], v[12:15]
	v_mfma_f32_16x16x32_bf16 v[4:7], v[160:163], v[212:215], v[4:7]
	v_mfma_f32_16x16x32_bf16 v[60:63], v[156:159], v[192:195], v[60:63]
	v_mfma_f32_16x16x32_bf16 v[52:55], v[164:167], v[192:195], v[52:55]
	v_mfma_f32_16x16x32_bf16 v[44:47], v[156:159], v[200:203], v[44:47]
	v_mfma_f32_16x16x32_bf16 v[36:39], v[164:167], v[200:203], v[36:39]
	v_mfma_f32_16x16x32_bf16 v[28:31], v[156:159], v[208:211], v[28:31]
	v_mfma_f32_16x16x32_bf16 v[20:23], v[164:167], v[208:211], v[20:23]
	v_mfma_f32_16x16x32_bf16 v[12:15], v[156:159], v[216:219], v[12:15]
	v_mfma_f32_16x16x32_bf16 v[4:7], v[164:167], v[216:219], v[4:7]
	s_setprio 0
	s_setprio 1
	v_mfma_f32_16x16x32_bf16 v[56:59], v[168:171], v[186:189], v[56:59]
	v_mfma_f32_16x16x32_bf16 v[48:51], v[176:179], v[186:189], v[48:51]
	v_mfma_f32_16x16x32_bf16 v[40:43], v[168:171], v[196:199], v[40:43]
	v_mfma_f32_16x16x32_bf16 v[32:35], v[176:179], v[196:199], v[32:35]
	v_mfma_f32_16x16x32_bf16 v[24:27], v[168:171], v[204:207], v[24:27]
	v_mfma_f32_16x16x32_bf16 v[16:19], v[176:179], v[204:207], v[16:19]
	v_mfma_f32_16x16x32_bf16 v[8:11], v[168:171], v[212:215], v[8:11]
	v_mfma_f32_16x16x32_bf16 v[0:3], v[176:179], v[212:215], v[0:3]
	v_mfma_f32_16x16x32_bf16 v[56:59], v[172:175], v[192:195], v[56:59]
	v_mfma_f32_16x16x32_bf16 v[48:51], v[182:185], v[192:195], v[48:51]
	v_mfma_f32_16x16x32_bf16 v[40:43], v[172:175], v[200:203], v[40:43]
	v_mfma_f32_16x16x32_bf16 v[32:35], v[182:185], v[200:203], v[32:35]
	v_mfma_f32_16x16x32_bf16 v[24:27], v[172:175], v[208:211], v[24:27]
	v_mfma_f32_16x16x32_bf16 v[16:19], v[182:185], v[208:211], v[16:19]
	v_mfma_f32_16x16x32_bf16 v[8:11], v[172:175], v[216:219], v[8:11]
	v_mfma_f32_16x16x32_bf16 v[0:3], v[182:185], v[216:219], v[0:3]
	s_setprio 0
	s_barrier
	s_add_i32 s93, 0, 0x18000
	s_add_i32 s94, 0, 0x1c000
	v_add_u32_e32 v164, s93, v147
	v_add_u32_e32 v181, s94, v147
	ds_read_b128 v[152:155], v164
	ds_read_b128 v[156:159], v164 offset:1024
	ds_read_b128 v[160:163], v164 offset:2048
	ds_read_b128 v[164:167], v164 offset:3072
	ds_read_b128 v[168:171], v181
	ds_read_b128 v[172:175], v181 offset:1024
	ds_read_b128 v[176:179], v181 offset:2048
	ds_read_b128 v[182:185], v181 offset:3072
	s_add_u32 s46, s46, 0x40000
	s_addc_u32 s47, s47, 0
	s_mov_b32 m0, s78
	v_lshl_add_u64 v[226:227], s[46:47], 0, v[134:135]
	ds_read_b128 v[186:189], v151 offset:32768
	ds_read_b128 v[192:195], v151 offset:33792
	ds_read_b128 v[196:199], v151 offset:34816
	ds_read_b128 v[200:203], v151 offset:35840
	ds_read_b128 v[204:207], v151 offset:36864
	ds_read_b128 v[208:211], v151 offset:37888
	ds_read_b128 v[212:215], v151 offset:38912
	ds_read_b128 v[216:219], v151 offset:39936
	global_load_lds_dwordx4 v[226:227], off
	v_lshl_add_u64 v[226:227], s[46:47], 0, v[130:131]
	s_mov_b32 m0, s79
	s_nop 0
	global_load_lds_dwordx4 v[226:227], off
	s_waitcnt vmcnt(8)
	s_waitcnt lgkmcnt(0)
	s_barrier
	s_setprio 1
	s_waitcnt lgkmcnt(0)
	v_mfma_f32_16x16x32_bf16 v[124:127], v[152:155], v[186:189], v[124:127]
	v_mfma_f32_16x16x32_bf16 v[116:119], v[160:163], v[186:189], v[116:119]
	v_mfma_f32_16x16x32_bf16 v[108:111], v[152:155], v[196:199], v[108:111]
	v_mfma_f32_16x16x32_bf16 v[100:103], v[160:163], v[196:199], v[100:103]
	v_mfma_f32_16x16x32_bf16 v[92:95], v[152:155], v[204:207], v[92:95]
	v_mfma_f32_16x16x32_bf16 v[84:87], v[160:163], v[204:207], v[84:87]
	v_mfma_f32_16x16x32_bf16 v[76:79], v[152:155], v[212:215], v[76:79]
	v_mfma_f32_16x16x32_bf16 v[68:71], v[160:163], v[212:215], v[68:71]
	v_mfma_f32_16x16x32_bf16 v[124:127], v[156:159], v[192:195], v[124:127]
	v_mfma_f32_16x16x32_bf16 v[116:119], v[164:167], v[192:195], v[116:119]
	v_mfma_f32_16x16x32_bf16 v[108:111], v[156:159], v[200:203], v[108:111]
	v_mfma_f32_16x16x32_bf16 v[100:103], v[164:167], v[200:203], v[100:103]
	v_mfma_f32_16x16x32_bf16 v[92:95], v[156:159], v[208:211], v[92:95]
	v_mfma_f32_16x16x32_bf16 v[84:87], v[164:167], v[208:211], v[84:87]
	v_mfma_f32_16x16x32_bf16 v[76:79], v[156:159], v[216:219], v[76:79]
	v_mfma_f32_16x16x32_bf16 v[68:71], v[164:167], v[216:219], v[68:71]
	s_setprio 0
	s_setprio 1
	v_mfma_f32_16x16x32_bf16 v[120:123], v[168:171], v[186:189], v[120:123]
	v_mfma_f32_16x16x32_bf16 v[112:115], v[176:179], v[186:189], v[112:115]
	v_mfma_f32_16x16x32_bf16 v[104:107], v[168:171], v[196:199], v[104:107]
	v_mfma_f32_16x16x32_bf16 v[96:99], v[176:179], v[196:199], v[96:99]
	v_mfma_f32_16x16x32_bf16 v[88:91], v[168:171], v[204:207], v[88:91]
	v_mfma_f32_16x16x32_bf16 v[80:83], v[176:179], v[204:207], v[80:83]
	v_mfma_f32_16x16x32_bf16 v[72:75], v[168:171], v[212:215], v[72:75]
	v_mfma_f32_16x16x32_bf16 v[64:67], v[176:179], v[212:215], v[64:67]
	v_mfma_f32_16x16x32_bf16 v[120:123], v[172:175], v[192:195], v[120:123]
	v_mfma_f32_16x16x32_bf16 v[112:115], v[182:185], v[192:195], v[112:115]
	v_mfma_f32_16x16x32_bf16 v[104:107], v[172:175], v[200:203], v[104:107]
	v_mfma_f32_16x16x32_bf16 v[96:99], v[182:185], v[200:203], v[96:99]
	v_mfma_f32_16x16x32_bf16 v[88:91], v[172:175], v[208:211], v[88:91]
	v_mfma_f32_16x16x32_bf16 v[80:83], v[182:185], v[208:211], v[80:83]
	v_mfma_f32_16x16x32_bf16 v[72:75], v[172:175], v[216:219], v[72:75]
	v_mfma_f32_16x16x32_bf16 v[64:67], v[182:185], v[216:219], v[64:67]
	s_setprio 0
	s_barrier
; __device__ __forceinline__ u32x2 pack4(f32x4 v) { u32x2 w; w.x = cvt_pk_bf16(v[0], v[1]); w.y = cvt_pk_bf16(v[2], v[3]); return w; }
; #define PG8_STAGE(bufoff, gbase, voff) do { _Pragma("unroll") for (int _i = 0; _i < 2; ++_i) \
;         __builtin_amdgcn_global_load_lds((const unsigned*)((const char*)(gbase) + (voff)[_i]), (PG8_LAS unsigned*)(lds + (bufoff) + ldsw + _i * 8192), 16, 0, 0); } while (0)
; #define PG8_LDA(dst, b, h) do { _Pragma("unroll") for (int m = 0; m < 4; ++m) _Pragma("unroll") for (int k = 0; k < 2; ++k) dst[m][k] = *(const PG8_LAS bf16x8*)(lds + PG8_SA(b, h) + aoff + m * 2048 + k * 1024); } while (0)
; #define PG8_MMA(ai, bj, At, Bt) do { __builtin_amdgcn_s_setprio(1); _Pragma("unroll") for (int m = 0; m < 4; ++m) _Pragma("unroll") for (int n = 0; n < 2; ++n) _Pragma("unroll") for (int k = 0; k < 2; ++k) \
;         acc[ai][bj][m][n] = __builtin_amdgcn_mfma_f32_16x16x32_bf16(Bt[n][k], At[m][k], acc[ai][bj][m][n], 0, 0, 0); __builtin_amdgcn_s_setprio(0); } while (0)
;     __device__ __forceinline__ void operator()(const f32x4 (&acc)[2][2][4][2], const Unit& u, int wr, int wc, int fr, int fq) const {
;     ...
;         for (int ai = 0; ai < 2; ++ai)
; #pragma unroll
;             for (int m = 0; m < 4; ++m) { const int row = row0 + ai * HALF + m * 16; bf16_t* rowp = (bf16_t*)(ws + WS_ACT) + (size_t)row * DFF + col0; u32x4e w;
; #pragma unroll
;                 for (int n = 0; n < 2; ++n) { const f32x4 a = acc[ai][0][m][n] * ri[ai][m], b = acc[ai][1][m][n] * ri[ai][m]; f32x4 o;
; #pragma unroll
;                     for (int i = 0; i < 4; ++i) o[i] = a[i] * __builtin_amdgcn_rcpf(1.0f + __builtin_amdgcn_exp2f(-a[i])) * b[i];
;                     const u32x2 p = pack4(o); w[2 * n] = p.x; w[2 * n + 1] = p.y; }
;                 *(u32x4e*)rowp = w; }
; template <class Epi, class Sched, bool ALIGN_EPI = false, bool SP2 = false>
; __device__ __forceinline__ void gemm_phase(PG8_LAS unsigned char* lds, const Gemm g, const Sched& S, const Epi& E) {
;     ...
;             PG8_WAIT_V(8); PG8_WAIT_L(0); PG8_BAR; PG8_MMA(0, 0, At, B0); PG8_MMA(0, 1, At, B1); PG8_BAR; PG8_SCHED;
;             PG8_LDA(At, 1, 1); PG8_STAGE(PG8_SB(1, 0), b3, voffB); PG8_STAGE(PG8_SB(1, 1), b3 + hstep, voffB); PG8_STAGE(PG8_SA(1, 0), a3, voffA);
;             PG8_WAIT_V(8); PG8_WAIT_L(0); PG8_BAR; PG8_MMA(1, 0, At, B0); PG8_MMA(1, 1, At, B1); PG8_BAR; PG8_SCHED;
	s_add_i32 s46, s93, s48
	v_lshl_add_u64 v[144:145], v[144:145], 0, s[6:7]
	s_mov_b32 m0, s46
	ds_read_b128 v[186:189], v151 offset:49152
	ds_read_b128 v[192:195], v151 offset:50176
	ds_read_b128 v[196:199], v151 offset:51200
	ds_read_b128 v[200:203], v151 offset:52224
	ds_read_b128 v[204:207], v151 offset:53248
	ds_read_b128 v[208:211], v151 offset:54272
	ds_read_b128 v[212:215], v151 offset:55296
	ds_read_b128 v[216:219], v151 offset:56320
	global_load_lds_dwordx4 v[144:145], off
	s_add_i32 m0, s46, 0x2000
	s_add_u32 s44, s44, 0x40080
	v_lshl_add_u64 v[144:145], v[220:221], 0, s[6:7]
	s_addc_u32 s45, s45, 0
	s_add_i32 s46, s94, s48
	global_load_lds_dwordx4 v[144:145], off
	v_lshl_add_u64 v[144:145], s[44:45], 0, v[132:133]
	s_mov_b32 m0, s46
	s_nop 0
	global_load_lds_dwordx4 v[144:145], off
	v_lshl_add_u64 v[144:145], s[44:45], 0, v[128:129]
	s_add_i32 m0, s46, 0x2000
	s_nop 0
	global_load_lds_dwordx4 v[144:145], off
	v_lshl_add_u64 v[144:145], v[222:223], 0, s[6:7]
	s_mov_b32 m0, s81
	s_nop 0
	global_load_lds_dwordx4 v[144:145], off
	v_lshl_add_u64 v[144:145], v[224:225], 0, s[6:7]
	s_mov_b32 m0, s82
	s_nop 0
	global_load_lds_dwordx4 v[144:145], off
	s_waitcnt vmcnt(8)
	s_waitcnt lgkmcnt(0)
	s_barrier
	s_setprio 1
	s_waitcnt lgkmcnt(0)
	v_mfma_f32_16x16x32_bf16 v[60:63], v[152:155], v[186:189], v[60:63]
	v_mfma_f32_16x16x32_bf16 v[52:55], v[160:163], v[186:189], v[52:55]
	v_mfma_f32_16x16x32_bf16 v[44:47], v[152:155], v[196:199], v[44:47]
	v_mfma_f32_16x16x32_bf16 v[36:39], v[160:163], v[196:199], v[36:39]
	v_mfma_f32_16x16x32_bf16 v[28:31], v[152:155], v[204:207], v[28:31]
	v_mfma_f32_16x16x32_bf16 v[20:23], v[160:163], v[204:207], v[20:23]
	v_mfma_f32_16x16x32_bf16 v[12:15], v[152:155], v[212:215], v[12:15]
	v_mfma_f32_16x16x32_bf16 v[4:7], v[160:163], v[212:215], v[4:7]
	v_mfma_f32_16x16x32_bf16 v[60:63], v[156:159], v[192:195], v[60:63]
	v_mfma_f32_16x16x32_bf16 v[52:55], v[164:167], v[192:195], v[52:55]
	v_mfma_f32_16x16x32_bf16 v[44:47], v[156:159], v[200:203], v[44:47]
	v_mfma_f32_16x16x32_bf16 v[36:39], v[164:167], v[200:203], v[36:39]
	v_mfma_f32_16x16x32_bf16 v[28:31], v[156:159], v[208:211], v[28:31]
	v_mfma_f32_16x16x32_bf16 v[20:23], v[164:167], v[208:211], v[20:23]
	v_mfma_f32_16x16x32_bf16 v[12:15], v[156:159], v[216:219], v[12:15]
	v_mfma_f32_16x16x32_bf16 v[4:7], v[164:167], v[216:219], v[4:7]
	s_setprio 0
	s_setprio 1
	v_mfma_f32_16x16x32_bf16 v[56:59], v[168:171], v[186:189], v[56:59]
	v_mfma_f32_16x16x32_bf16 v[48:51], v[176:179], v[186:189], v[48:51]
	v_mfma_f32_16x16x32_bf16 v[40:43], v[168:171], v[196:199], v[40:43]
	v_mfma_f32_16x16x32_bf16 v[32:35], v[176:179], v[196:199], v[32:35]
	v_mfma_f32_16x16x32_bf16 v[24:27], v[168:171], v[204:207], v[24:27]
	v_mfma_f32_16x16x32_bf16 v[16:19], v[176:179], v[204:207], v[16:19]
	v_mfma_f32_16x16x32_bf16 v[8:11], v[168:171], v[212:215], v[8:11]
	v_mfma_f32_16x16x32_bf16 v[0:3], v[176:179], v[212:215], v[0:3]
	v_mfma_f32_16x16x32_bf16 v[56:59], v[172:175], v[192:195], v[56:59]
	v_mfma_f32_16x16x32_bf16 v[48:51], v[182:185], v[192:195], v[48:51]
	v_mfma_f32_16x16x32_bf16 v[40:43], v[172:175], v[200:203], v[40:43]
	v_mfma_f32_16x16x32_bf16 v[32:35], v[182:185], v[200:203], v[32:35]
	v_mfma_f32_16x16x32_bf16 v[24:27], v[172:175], v[208:211], v[24:27]
	v_mfma_f32_16x16x32_bf16 v[16:19], v[182:185], v[208:211], v[16:19]
	v_mfma_f32_16x16x32_bf16 v[8:11], v[172:175], v[216:219], v[8:11]
	v_mfma_f32_16x16x32_bf16 v[0:3], v[182:185], v[216:219], v[0:3]
	s_setprio 0
	s_barrier
	s_add_i32 s92, s92, 2
	s_add_u32 s42, s42, 0x100
	s_addc_u32 s43, s43, 0
	s_add_u32 s90, s90, 0x100
	s_addc_u32 s91, s91, 0
	s_cmp_gt_u32 s92, 13
	s_cbranch_scc0 .LBB0_192
	s_and_b64 vcc, exec, s[18:19]
	s_cbranch_vccz .LBB0_195
.LBB0_195:
	v_exp_f32_e64 v156, -v124
	v_exp_f32_e64 v157, -v125
	v_exp_f32_e64 v158, -v126
	v_exp_f32_e64 v159, -v127
	v_add_f32_e32 v156, 1.0, v156
	v_add_f32_e32 v157, 1.0, v157
	v_rcp_f32_e32 v156, v156
	v_rcp_f32_e32 v157, v157
	v_add_f32_e32 v158, 1.0, v158
	v_add_f32_e32 v159, 1.0, v159
	v_rcp_f32_e32 v158, v158
	v_rcp_f32_e32 v159, v159
	v_pk_mul_f32 v[124:125], v[124:125], v[156:157]
	v_lshl_or_b32 v154, s87, 7, v148
	v_pk_mul_f32 v[120:121], v[124:125], v[120:121]
	v_pk_mul_f32 v[124:125], v[126:127], v[158:159]
	v_exp_f32_e64 v126, -v116
	v_cvt_pk_bf16_f32 v120, v120, v121
	v_exp_f32_e64 v121, -v117
	v_pk_mul_f32 v[122:123], v[124:125], v[122:123]
	v_add_f32_e32 v124, 1.0, v126
	v_exp_f32_e64 v126, -v118
	v_exp_f32_e64 v127, -v119
	v_add_f32_e32 v121, 1.0, v121
	v_rcp_f32_e32 v125, v121
	v_add_f32_e32 v121, 1.0, v126
	v_rcp_f32_e32 v124, v124
	v_rcp_f32_e32 v126, v121
	v_add_f32_e32 v121, 1.0, v127
	v_rcp_f32_e32 v127, v121
	v_pk_mul_f32 v[116:117], v[116:117], v[124:125]
	v_lshl_add_u32 v152, s40, 8, v146
	v_pk_mul_f32 v[112:113], v[116:117], v[112:113]
	v_pk_mul_f32 v[116:117], v[118:119], v[126:127]
	v_ashrrev_i32_e32 v155, 31, v154
	v_mov_b64_e32 v[144:145], s[16:17]
	v_pk_mul_f32 v[114:115], v[116:117], v[114:115]
	v_exp_f32_e64 v116, -v108
	v_mad_i64_i32 v[160:161], s[42:43], v152, s86, v[144:145]
	v_cvt_pk_bf16_f32 v121, v122, v123
	v_cvt_pk_bf16_f32 v122, v112, v113
	v_lshlrev_b64 v[112:113], 1, v[154:155]
	v_cvt_pk_bf16_f32 v123, v114, v115
	v_lshl_add_u64 v[114:115], v[160:161], 0, v[112:113]
	global_store_dwordx4 v[114:115], v[120:123], off
	v_exp_f32_e64 v115, -v109
	v_add_f32_e32 v114, 1.0, v116
	v_exp_f32_e64 v116, -v110
	v_exp_f32_e64 v117, -v111
	v_add_f32_e32 v115, 1.0, v115
	v_rcp_f32_e32 v114, v114
	v_rcp_f32_e32 v115, v115
	v_add_f32_e32 v116, 1.0, v116
	v_add_f32_e32 v117, 1.0, v117
	v_rcp_f32_e32 v116, v116
	v_rcp_f32_e32 v117, v117
; __device__ __forceinline__ u32x2 pack4(f32x4 v) { u32x2 w; w.x = cvt_pk_bf16(v[0], v[1]); w.y = cvt_pk_bf16(v[2], v[3]); return w; }
;     __device__ __forceinline__ void operator()(const f32x4 (&acc)[2][2][4][2], const Unit& u, int wr, int wc, int fr, int fq) const {
;     ...
;         for (int ai = 0; ai < 2; ++ai)
; #pragma unroll
;             for (int m = 0; m < 4; ++m) { const int row = row0 + ai * HALF + m * 16; bf16_t* rowp = (bf16_t*)(ws + WS_ACT) + (size_t)row * DFF + col0; u32x4e w;
; #pragma unroll
;                 for (int n = 0; n < 2; ++n) { const f32x4 a = acc[ai][0][m][n] * ri[ai][m], b = acc[ai][1][m][n] * ri[ai][m]; f32x4 o;
; #pragma unroll
;                     for (int i = 0; i < 4; ++i) o[i] = a[i] * __builtin_amdgcn_rcpf(1.0f + __builtin_amdgcn_exp2f(-a[i])) * b[i];
;                     const u32x2 p = pack4(o); w[2 * n] = p.x; w[2 * n + 1] = p.y; }
;                 *(u32x4e*)rowp = w; }
	v_pk_mul_f32 v[108:109], v[108:109], v[114:115]
	v_or_b32_e32 v162, 16, v152
	v_pk_mul_f32 v[104:105], v[108:109], v[104:105]
	v_pk_mul_f32 v[108:109], v[110:111], v[116:117]
	v_exp_f32_e64 v110, -v100
	v_cvt_pk_bf16_f32 v104, v104, v105
	v_exp_f32_e64 v105, -v101
	v_pk_mul_f32 v[106:107], v[108:109], v[106:107]
	v_add_f32_e32 v108, 1.0, v110
	v_exp_f32_e64 v110, -v102
	v_exp_f32_e64 v111, -v103
	v_add_f32_e32 v105, 1.0, v105
	v_rcp_f32_e32 v109, v105
	v_add_f32_e32 v105, 1.0, v110
	v_rcp_f32_e32 v108, v108
	v_rcp_f32_e32 v110, v105
	v_add_f32_e32 v105, 1.0, v111
	v_rcp_f32_e32 v111, v105
	v_pk_mul_f32 v[100:101], v[100:101], v[108:109]
	v_cvt_pk_bf16_f32 v105, v106, v107
	v_pk_mul_f32 v[96:97], v[100:101], v[96:97]
	v_pk_mul_f32 v[100:101], v[102:103], v[110:111]
	v_mad_i64_i32 v[118:119], s[42:43], v162, s86, v[144:145]
	v_pk_mul_f32 v[98:99], v[100:101], v[98:99]
	v_cvt_pk_bf16_f32 v106, v96, v97
	v_cvt_pk_bf16_f32 v107, v98, v99
	v_exp_f32_e64 v98, -v92
	v_lshl_add_u64 v[96:97], v[118:119], 0, v[112:113]
	global_store_dwordx4 v[96:97], v[104:107], off
	v_exp_f32_e64 v97, -v93
	v_add_f32_e32 v96, 1.0, v98
	v_exp_f32_e64 v98, -v94
	v_exp_f32_e64 v99, -v95
	v_add_f32_e32 v97, 1.0, v97
	v_rcp_f32_e32 v96, v96
	v_rcp_f32_e32 v97, v97
	v_add_f32_e32 v98, 1.0, v98
	v_add_f32_e32 v99, 1.0, v99
	v_rcp_f32_e32 v98, v98
	v_rcp_f32_e32 v99, v99
	v_pk_mul_f32 v[92:93], v[92:93], v[96:97]
	v_or_b32_e32 v163, 32, v152
	v_pk_mul_f32 v[88:89], v[92:93], v[88:89]
	v_pk_mul_f32 v[92:93], v[94:95], v[98:99]
	v_exp_f32_e64 v94, -v84
	v_cvt_pk_bf16_f32 v88, v88, v89
	v_exp_f32_e64 v89, -v85
	v_pk_mul_f32 v[90:91], v[92:93], v[90:91]
	v_add_f32_e32 v92, 1.0, v94
	v_exp_f32_e64 v94, -v86
	v_exp_f32_e64 v95, -v87
	v_add_f32_e32 v89, 1.0, v89
	v_rcp_f32_e32 v93, v89
	v_add_f32_e32 v89, 1.0, v94
	v_rcp_f32_e32 v92, v92
	v_rcp_f32_e32 v94, v89
	v_add_f32_e32 v89, 1.0, v95
	v_rcp_f32_e32 v95, v89
	v_pk_mul_f32 v[84:85], v[84:85], v[92:93]
	v_cvt_pk_bf16_f32 v89, v90, v91
	v_pk_mul_f32 v[80:81], v[84:85], v[80:81]
	v_pk_mul_f32 v[84:85], v[86:87], v[94:95]
	v_mad_i64_i32 v[100:101], s[42:43], v163, s86, v[144:145]
	v_pk_mul_f32 v[82:83], v[84:85], v[82:83]
	v_cvt_pk_bf16_f32 v90, v80, v81
	v_cvt_pk_bf16_f32 v91, v82, v83
	v_exp_f32_e64 v82, -v76
	v_lshl_add_u64 v[80:81], v[100:101], 0, v[112:113]
	global_store_dwordx4 v[80:81], v[88:91], off
	v_exp_f32_e64 v81, -v77
	v_add_f32_e32 v80, 1.0, v82
	v_exp_f32_e64 v82, -v78
	v_exp_f32_e64 v83, -v79
	v_add_f32_e32 v81, 1.0, v81
	v_rcp_f32_e32 v80, v80
	v_rcp_f32_e32 v81, v81
	v_add_f32_e32 v82, 1.0, v82
	v_add_f32_e32 v83, 1.0, v83
	v_rcp_f32_e32 v82, v82
	v_rcp_f32_e32 v83, v83
	v_pk_mul_f32 v[76:77], v[76:77], v[80:81]
	v_or_b32_e32 v164, 48, v152
	v_pk_mul_f32 v[72:73], v[76:77], v[72:73]
	v_pk_mul_f32 v[76:77], v[78:79], v[82:83]
	v_exp_f32_e64 v78, -v68
	v_cvt_pk_bf16_f32 v72, v72, v73
	v_exp_f32_e64 v73, -v69
	v_pk_mul_f32 v[74:75], v[76:77], v[74:75]
	v_add_f32_e32 v76, 1.0, v78
	v_exp_f32_e64 v78, -v70
	v_exp_f32_e64 v79, -v71
	v_add_f32_e32 v73, 1.0, v73
	v_rcp_f32_e32 v77, v73
	v_add_f32_e32 v73, 1.0, v78
	v_rcp_f32_e32 v76, v76
	v_rcp_f32_e32 v78, v73
	v_add_f32_e32 v73, 1.0, v79
	v_rcp_f32_e32 v79, v73
	v_pk_mul_f32 v[68:69], v[68:69], v[76:77]
	v_cvt_pk_bf16_f32 v73, v74, v75
	v_pk_mul_f32 v[64:65], v[68:69], v[64:65]
	v_pk_mul_f32 v[68:69], v[70:71], v[78:79]
	v_mad_i64_i32 v[84:85], s[42:43], v164, s86, v[144:145]
	v_pk_mul_f32 v[66:67], v[68:69], v[66:67]
	v_cvt_pk_bf16_f32 v74, v64, v65
	v_cvt_pk_bf16_f32 v75, v66, v67
	v_exp_f32_e64 v66, -v60
	v_lshl_add_u64 v[64:65], v[84:85], 0, v[112:113]
	global_store_dwordx4 v[64:65], v[72:75], off
	v_exp_f32_e64 v65, -v61
	v_add_f32_e32 v64, 1.0, v66
	v_exp_f32_e64 v66, -v62
	v_exp_f32_e64 v67, -v63
	v_add_f32_e32 v65, 1.0, v65
	v_rcp_f32_e32 v64, v64
	v_rcp_f32_e32 v65, v65
	v_add_f32_e32 v66, 1.0, v66
	v_add_f32_e32 v67, 1.0, v67
	v_rcp_f32_e32 v66, v66
	v_rcp_f32_e32 v67, v67
	v_pk_mul_f32 v[60:61], v[60:61], v[64:65]
	v_add_u32_e32 v153, 0x80, v152
	v_pk_mul_f32 v[56:57], v[60:61], v[56:57]
	v_pk_mul_f32 v[60:61], v[62:63], v[66:67]
	v_exp_f32_e64 v62, -v52
	v_cvt_pk_bf16_f32 v56, v56, v57
	v_exp_f32_e64 v57, -v53
	v_pk_mul_f32 v[58:59], v[60:61], v[58:59]
	v_add_f32_e32 v60, 1.0, v62
	v_exp_f32_e64 v62, -v54
	v_exp_f32_e64 v63, -v55
	v_add_f32_e32 v57, 1.0, v57
	v_rcp_f32_e32 v61, v57
	v_add_f32_e32 v57, 1.0, v62
	v_rcp_f32_e32 v60, v60
	v_rcp_f32_e32 v62, v57
	v_add_f32_e32 v57, 1.0, v63
	v_rcp_f32_e32 v63, v57
	v_pk_mul_f32 v[52:53], v[52:53], v[60:61]
	v_cvt_pk_bf16_f32 v57, v58, v59
	v_pk_mul_f32 v[48:49], v[52:53], v[48:49]
	v_pk_mul_f32 v[52:53], v[54:55], v[62:63]
	v_mad_i64_i32 v[68:69], s[42:43], v153, s86, v[144:145]
	v_pk_mul_f32 v[50:51], v[52:53], v[50:51]
	v_cvt_pk_bf16_f32 v58, v48, v49
	v_cvt_pk_bf16_f32 v59, v50, v51
	v_exp_f32_e64 v50, -v44
	v_lshl_add_u64 v[48:49], v[68:69], 0, v[112:113]
	global_store_dwordx4 v[48:49], v[56:59], off
	v_exp_f32_e64 v49, -v45
	v_add_f32_e32 v48, 1.0, v50
	v_exp_f32_e64 v50, -v46
	v_exp_f32_e64 v51, -v47
	v_add_f32_e32 v49, 1.0, v49
	v_rcp_f32_e32 v48, v48
	v_rcp_f32_e32 v49, v49
	v_add_f32_e32 v50, 1.0, v50
	v_add_f32_e32 v51, 1.0, v51
	v_rcp_f32_e32 v50, v50
	v_rcp_f32_e32 v51, v51
; __device__ __forceinline__ u32x2 pack4(f32x4 v) { u32x2 w; w.x = cvt_pk_bf16(v[0], v[1]); w.y = cvt_pk_bf16(v[2], v[3]); return w; }
;     __device__ __forceinline__ void operator()(const f32x4 (&acc)[2][2][4][2], const Unit& u, int wr, int wc, int fr, int fq) const {
;     ...
;             for (int m = 0; m < 4; ++m) { const int row = row0 + ai * HALF + m * 16; bf16_t* rowp = (bf16_t*)(ws + WS_ACT) + (size_t)row * DFF + col0; u32x4e w;
; #pragma unroll
;                 for (int n = 0; n < 2; ++n) { const f32x4 a = acc[ai][0][m][n] * ri[ai][m], b = acc[ai][1][m][n] * ri[ai][m]; f32x4 o;
; #pragma unroll
;                     for (int i = 0; i < 4; ++i) o[i] = a[i] * __builtin_amdgcn_rcpf(1.0f + __builtin_amdgcn_exp2f(-a[i])) * b[i];
;                     const u32x2 p = pack4(o); w[2 * n] = p.x; w[2 * n + 1] = p.y; }
;                 *(u32x4e*)rowp = w; }
; __device__ __forceinline__ void xcd_barrier(const XcdBarrier& b) {
;     asm volatile("s_waitcnt vmcnt(0)" ::: "memory");
;     __syncthreads();
;     if (threadIdx.x == 0) {
;         unsigned* bar = b.bar;
;         __builtin_amdgcn_s_waitcnt(0);
;         unsigned nloc = b.st[0], nx = b.st[1];
;         if (nloc == 0u) { xcd_barrier_complete(bar, b.x, nloc, nx); b.st[0] = nloc; b.st[1] = nx; }
	v_pk_mul_f32 v[44:45], v[44:45], v[48:49]
	v_add_u32_e32 v52, 0x90, v152
	v_pk_mul_f32 v[40:41], v[44:45], v[40:41]
	v_pk_mul_f32 v[44:45], v[46:47], v[50:51]
	v_exp_f32_e64 v46, -v36
	v_cvt_pk_bf16_f32 v40, v40, v41
	v_exp_f32_e64 v41, -v37
	v_pk_mul_f32 v[42:43], v[44:45], v[42:43]
	v_add_f32_e32 v44, 1.0, v46
	v_exp_f32_e64 v46, -v38
	v_exp_f32_e64 v47, -v39
	v_add_f32_e32 v41, 1.0, v41
	v_rcp_f32_e32 v45, v41
	v_add_f32_e32 v41, 1.0, v46
	v_rcp_f32_e32 v44, v44
	v_rcp_f32_e32 v46, v41
	v_add_f32_e32 v41, 1.0, v47
	v_rcp_f32_e32 v47, v41
	v_pk_mul_f32 v[36:37], v[36:37], v[44:45]
	v_cvt_pk_bf16_f32 v41, v42, v43
	v_pk_mul_f32 v[32:33], v[36:37], v[32:33]
	v_pk_mul_f32 v[36:37], v[38:39], v[46:47]
	v_mad_i64_i32 v[52:53], s[42:43], v52, s86, v[144:145]
	v_pk_mul_f32 v[34:35], v[36:37], v[34:35]
	v_cvt_pk_bf16_f32 v42, v32, v33
	v_cvt_pk_bf16_f32 v43, v34, v35
	v_exp_f32_e64 v34, -v28
	v_lshl_add_u64 v[32:33], v[52:53], 0, v[112:113]
	global_store_dwordx4 v[32:33], v[40:43], off
	v_exp_f32_e64 v33, -v29
	v_add_f32_e32 v32, 1.0, v34
	v_exp_f32_e64 v34, -v30
	v_exp_f32_e64 v35, -v31
	v_add_f32_e32 v33, 1.0, v33
	v_rcp_f32_e32 v32, v32
	v_rcp_f32_e32 v33, v33
	v_add_f32_e32 v34, 1.0, v34
	v_add_f32_e32 v35, 1.0, v35
	v_rcp_f32_e32 v34, v34
	v_rcp_f32_e32 v35, v35
	v_pk_mul_f32 v[28:29], v[28:29], v[32:33]
	v_add_u32_e32 v36, 0xa0, v152
	v_pk_mul_f32 v[24:25], v[28:29], v[24:25]
	v_pk_mul_f32 v[28:29], v[30:31], v[34:35]
	v_exp_f32_e64 v30, -v20
	v_cvt_pk_bf16_f32 v24, v24, v25
	v_exp_f32_e64 v25, -v21
	v_pk_mul_f32 v[26:27], v[28:29], v[26:27]
	v_add_f32_e32 v28, 1.0, v30
	v_exp_f32_e64 v30, -v22
	v_exp_f32_e64 v31, -v23
	v_add_f32_e32 v25, 1.0, v25
	v_rcp_f32_e32 v29, v25
	v_add_f32_e32 v25, 1.0, v30
	v_rcp_f32_e32 v28, v28
	v_rcp_f32_e32 v30, v25
	v_add_f32_e32 v25, 1.0, v31
	v_rcp_f32_e32 v31, v25
	v_pk_mul_f32 v[20:21], v[20:21], v[28:29]
	v_cvt_pk_bf16_f32 v25, v26, v27
	v_pk_mul_f32 v[16:17], v[20:21], v[16:17]
	v_pk_mul_f32 v[20:21], v[22:23], v[30:31]
	v_mad_i64_i32 v[36:37], s[42:43], v36, s86, v[144:145]
	v_pk_mul_f32 v[18:19], v[20:21], v[18:19]
	v_cvt_pk_bf16_f32 v26, v16, v17
	v_cvt_pk_bf16_f32 v27, v18, v19
	v_exp_f32_e64 v18, -v12
	v_lshl_add_u64 v[16:17], v[36:37], 0, v[112:113]
	global_store_dwordx4 v[16:17], v[24:27], off
	v_exp_f32_e64 v17, -v13
	v_add_f32_e32 v16, 1.0, v18
	v_exp_f32_e64 v18, -v14
	v_exp_f32_e64 v19, -v15
	v_add_f32_e32 v17, 1.0, v17
	v_rcp_f32_e32 v16, v16
	v_rcp_f32_e32 v17, v17
	v_add_f32_e32 v18, 1.0, v18
	v_add_f32_e32 v19, 1.0, v19
	v_rcp_f32_e32 v18, v18
	v_rcp_f32_e32 v19, v19
	v_pk_mul_f32 v[12:13], v[12:13], v[16:17]
	v_add_u32_e32 v20, 0xb0, v152
	v_pk_mul_f32 v[8:9], v[12:13], v[8:9]
	v_pk_mul_f32 v[12:13], v[14:15], v[18:19]
	v_exp_f32_e64 v14, -v4
	v_cvt_pk_bf16_f32 v8, v8, v9
	v_exp_f32_e64 v9, -v5
	v_pk_mul_f32 v[10:11], v[12:13], v[10:11]
	v_add_f32_e32 v12, 1.0, v14
	v_exp_f32_e64 v14, -v6
	v_exp_f32_e64 v15, -v7
	v_add_f32_e32 v9, 1.0, v9
	v_rcp_f32_e32 v13, v9
	v_add_f32_e32 v9, 1.0, v14
	v_rcp_f32_e32 v12, v12
	v_rcp_f32_e32 v14, v9
	v_add_f32_e32 v9, 1.0, v15
	v_rcp_f32_e32 v15, v9
	v_pk_mul_f32 v[4:5], v[4:5], v[12:13]
	v_mad_i64_i32 v[20:21], s[42:43], v20, s86, v[144:145]
	v_pk_mul_f32 v[0:1], v[4:5], v[0:1]
	v_pk_mul_f32 v[4:5], v[6:7], v[14:15]
	v_cvt_pk_bf16_f32 v9, v10, v11
	v_pk_mul_f32 v[2:3], v[4:5], v[2:3]
	v_cvt_pk_bf16_f32 v10, v0, v1
	v_cvt_pk_bf16_f32 v11, v2, v3
	v_lshl_add_u64 v[0:1], v[20:21], 0, v[112:113]
	s_andn2_b64 vcc, exec, s[2:3]
	s_mov_b64 s[2:3], -1
	global_store_dwordx4 v[0:1], v[8:11], off
	s_cbranch_vccnz .LBB0_188
	s_andn2_b64 vcc, exec, s[0:1]
	s_cbranch_vccnz .LBB0_187
	s_branch .LBB0_187
.LBB0_198:
	s_waitcnt vmcnt(0)
	s_and_b64 vcc, exec, s[18:19]
	s_cbranch_vccz .Lna_p1
	s_barrier
.Lna_p1:
	s_barrier
.LBB0_199:
	s_waitcnt vmcnt(0)
	s_waitcnt vmcnt(0)
	s_barrier
	s_mov_b64 s[0:1], exec
	v_readlane_b32 s2, v255, 1
	v_readlane_b32 s3, v255, 2
	s_and_b64 s[2:3], s[0:1], s[2:3]
	s_mov_b64 exec, s[2:3]
	s_cbranch_execz .LBB0_251
	s_add_i32 s2, 0, 0x20160
	v_mov_b32_e32 v0, s2
	s_waitcnt vmcnt(0) expcnt(0) lgkmcnt(0)
	ds_read_b32 v2, v0
	s_add_i32 s2, 0, 0x20164
	v_mov_b32_e32 v0, s2
	ds_read_b32 v0, v0
	s_waitcnt lgkmcnt(1)
	v_cmp_ne_u32_e32 vcc, 0, v2
	s_cbranch_vccnz .LBB0_215
	s_add_u32 s2, s58, 0x4200
	s_addc_u32 s3, s59, 0
	s_add_u32 s4, s58, 0x4400
	s_addc_u32 s5, s59, 0
	s_add_u32 s6, s58, 0x4500
	s_addc_u32 s7, s59, 0
	s_add_u32 s18, s58, 0x4600
	s_addc_u32 s19, s59, 0
	s_add_u32 s20, s58, 0x4700
	s_addc_u32 s21, s59, 0
	s_add_u32 s22, s58, 0x4800
	s_addc_u32 s23, s59, 0
	s_add_u32 s24, s58, 0x4900
	s_addc_u32 s25, s59, 0
	s_add_u32 s26, s58, 0x4a00
	s_addc_u32 s27, s59, 0
	s_add_u32 s40, s58, 0x4b00
	s_addc_u32 s41, s59, 0
	s_add_u32 s42, s58, 0x4c00
	s_addc_u32 s43, s59, 0
	s_add_u32 s44, s58, 0x4d00
	s_addc_u32 s45, s59, 0
	s_add_u32 s46, s58, 0x4e00
	s_addc_u32 s47, s59, 0
	s_add_u32 s48, s58, 0x4f00
	s_addc_u32 s49, s59, 0
	s_add_u32 s78, s58, 0x5000
	s_addc_u32 s79, s59, 0
	s_add_u32 s80, s58, 0x5100
	s_addc_u32 s81, s59, 0
	s_add_u32 s82, s58, 0x5200
	s_addc_u32 s83, s59, 0
	s_mul_i32 s60, s97, s11
	s_add_u32 s84, s58, 0x5300
	s_mul_i32 s60, s60, s96
	s_addc_u32 s85, s59, 0
	s_mov_b32 s61, 1
	v_mov_b32_e32 v16, 0
	s_branch .LBB0_203

; #define PG8_STAGE(bufoff, gbase, voff) do { _Pragma("unroll") for (int _i = 0; _i < 2; ++_i) \
;         __builtin_amdgcn_global_load_lds((const unsigned*)((const char*)(gbase) + (voff)[_i]), (PG8_LAS unsigned*)(lds + (bufoff) + ldsw + _i * 8192), 16, 0, 0); } while (0)
; #define PG8_LDA(dst, b, h) do { _Pragma("unroll") for (int m = 0; m < 4; ++m) _Pragma("unroll") for (int k = 0; k < 2; ++k) dst[m][k] = *(const PG8_LAS bf16x8*)(lds + PG8_SA(b, h) + aoff + m * 2048 + k * 1024); } while (0)
; #define PG8_LDB(dst, b, h) do { _Pragma("unroll") for (int n = 0; n < 2; ++n) _Pragma("unroll") for (int k = 0; k < 2; ++k) dst[n][k] = *(const PG8_LAS bf16x8*)(lds + PG8_SB(b, h) + boff + n * 2048 + k * 1024); } while (0)
; #define PG8_MMA(ai, bj, At, Bt) do { __builtin_amdgcn_s_setprio(1); _Pragma("unroll") for (int m = 0; m < 4; ++m) _Pragma("unroll") for (int n = 0; n < 2; ++n) _Pragma("unroll") for (int k = 0; k < 2; ++k) \
;         acc[ai][bj][m][n] = __builtin_amdgcn_mfma_f32_16x16x32_bf16(Bt[n][k], At[m][k], acc[ai][bj][m][n], 0, 0, 0); __builtin_amdgcn_s_setprio(0); } while (0)
; #define PG8_WAIT_V(n) asm volatile("s_waitcnt vmcnt(" #n ")" ::: "memory")
; #define PG8_WAIT_L(n) asm volatile("s_waitcnt lgkmcnt(" #n ")" ::: "memory")
; #define PG8_BAR __builtin_amdgcn_s_barrier()
; #define PG8_SCHED __builtin_amdgcn_sched_barrier(0)
; template <class Epi, class Sched, bool ALIGN_EPI = false, bool SP2 = false>
; __device__ __forceinline__ void gemm_phase(PG8_LAS unsigned char* lds, const Gemm g, const Sched& S, const Epi& E) {
;     ...
;             PG8_LDB(B0, 0, 0); PG8_LDB(B1, 0, 1); PG8_SCHED; PG8_LDA(At, 0, 0); PG8_STAGE(PG8_SA(1, 1), a1 + hstep, voffA);
;             PG8_WAIT_V(8); PG8_WAIT_L(0); PG8_BAR; PG8_MMA(0, 0, At, B0); PG8_MMA(0, 1, At, B1); PG8_BAR; PG8_SCHED;
;             PG8_LDA(At, 0, 1); PG8_STAGE(PG8_SB(0, 0), b2, voffB); PG8_STAGE(PG8_SB(0, 1), b2 + hstep, voffB); PG8_STAGE(PG8_SA(0, 0), a2, voffA);
;             PG8_WAIT_V(8); PG8_WAIT_L(0); PG8_BAR; PG8_MMA(1, 0, At, B0); PG8_MMA(1, 1, At, B1); PG8_BAR; PG8_SCHED;
.LBB0_895:
	ds_read_b128 v[128:131], v183
	ds_read_b128 v[132:135], v183 offset:1024
	ds_read_b128 v[136:139], v183 offset:2048
	ds_read_b128 v[140:143], v183 offset:3072
	ds_read_b128 v[162:165], v184
	ds_read_b128 v[166:169], v184 offset:1024
	ds_read_b128 v[170:173], v184 offset:2048
	ds_read_b128 v[174:177], v184 offset:3072
	s_add_u32 s26, s4, 0xfffc0080
	s_addc_u32 s27, s5, -1
	s_cmp_eq_u32 s67, 12
	s_cselect_b32 s37, s1, s27
	s_cselect_b32 s36, s21, s26
	s_cselect_b32 s27, s19, s66
	s_cselect_b32 s26, s60, s61
	v_lshl_add_u64 v[222:223], s[4:5], 0, v[154:155]
	s_add_i32 m0, s41, 0xc000
	ds_read_b128 v[190:193], v185
	ds_read_b128 v[194:197], v185 offset:1024
	ds_read_b128 v[198:201], v185 offset:2048
	ds_read_b128 v[202:205], v185 offset:3072
	ds_read_b128 v[206:209], v185 offset:4096
	ds_read_b128 v[210:213], v185 offset:5120
	ds_read_b128 v[214:217], v185 offset:6144
	ds_read_b128 v[218:221], v185 offset:7168
	global_load_lds_dwordx4 v[222:223], off
	v_lshl_add_u64 v[222:223], s[4:5], 0, v[156:157]
	s_add_i32 m0, s41, 0xe000
	s_nop 0
	global_load_lds_dwordx4 v[222:223], off
	s_waitcnt vmcnt(8)
	s_waitcnt lgkmcnt(0)
	s_barrier
	s_setprio 1
	s_waitcnt lgkmcnt(0)
	v_mfma_f32_16x16x32_bf16 v[124:127], v[128:131], v[190:193], v[124:127]
	v_mfma_f32_16x16x32_bf16 v[120:123], v[136:139], v[190:193], v[120:123]
	v_mfma_f32_16x16x32_bf16 v[108:111], v[128:131], v[198:201], v[108:111]
	v_mfma_f32_16x16x32_bf16 v[104:107], v[136:139], v[198:201], v[104:107]
	v_mfma_f32_16x16x32_bf16 v[92:95], v[128:131], v[206:209], v[92:95]
	v_mfma_f32_16x16x32_bf16 v[88:91], v[136:139], v[206:209], v[88:91]
	v_mfma_f32_16x16x32_bf16 v[76:79], v[128:131], v[214:217], v[76:79]
	v_mfma_f32_16x16x32_bf16 v[72:75], v[136:139], v[214:217], v[72:75]
	v_mfma_f32_16x16x32_bf16 v[124:127], v[132:135], v[194:197], v[124:127]
	v_mfma_f32_16x16x32_bf16 v[120:123], v[140:143], v[194:197], v[120:123]
	v_mfma_f32_16x16x32_bf16 v[108:111], v[132:135], v[202:205], v[108:111]
	v_mfma_f32_16x16x32_bf16 v[104:107], v[140:143], v[202:205], v[104:107]
	v_mfma_f32_16x16x32_bf16 v[92:95], v[132:135], v[210:213], v[92:95]
	v_mfma_f32_16x16x32_bf16 v[88:91], v[140:143], v[210:213], v[88:91]
	v_mfma_f32_16x16x32_bf16 v[76:79], v[132:135], v[218:221], v[76:79]
	v_mfma_f32_16x16x32_bf16 v[72:75], v[140:143], v[218:221], v[72:75]
	s_setprio 0
	s_setprio 1
	v_mfma_f32_16x16x32_bf16 v[116:119], v[162:165], v[190:193], v[116:119]
	v_mfma_f32_16x16x32_bf16 v[112:115], v[170:173], v[190:193], v[112:115]
	v_mfma_f32_16x16x32_bf16 v[100:103], v[162:165], v[198:201], v[100:103]
	v_mfma_f32_16x16x32_bf16 v[96:99], v[170:173], v[198:201], v[96:99]
	v_mfma_f32_16x16x32_bf16 v[84:87], v[162:165], v[206:209], v[84:87]
	v_mfma_f32_16x16x32_bf16 v[80:83], v[170:173], v[206:209], v[80:83]
	v_mfma_f32_16x16x32_bf16 v[68:71], v[162:165], v[214:217], v[68:71]
	v_mfma_f32_16x16x32_bf16 v[64:67], v[170:173], v[214:217], v[64:67]
	v_mfma_f32_16x16x32_bf16 v[116:119], v[166:169], v[194:197], v[116:119]
	v_mfma_f32_16x16x32_bf16 v[112:115], v[174:177], v[194:197], v[112:115]
	v_mfma_f32_16x16x32_bf16 v[100:103], v[166:169], v[202:205], v[100:103]
	v_mfma_f32_16x16x32_bf16 v[96:99], v[174:177], v[202:205], v[96:99]
	v_mfma_f32_16x16x32_bf16 v[84:87], v[166:169], v[210:213], v[84:87]
	v_mfma_f32_16x16x32_bf16 v[80:83], v[174:177], v[210:213], v[80:83]
	v_mfma_f32_16x16x32_bf16 v[68:71], v[166:169], v[218:221], v[68:71]
	v_mfma_f32_16x16x32_bf16 v[64:67], v[174:177], v[218:221], v[64:67]
	s_setprio 0
	s_barrier
	s_add_i32 s68, s49, s38
	v_lshl_add_u64 v[222:223], s[26:27], 0, v[148:149]
	s_mov_b32 m0, s68
	ds_read_b128 v[190:193], v185 offset:16384
	ds_read_b128 v[194:197], v185 offset:17408
	ds_read_b128 v[198:201], v185 offset:18432
	ds_read_b128 v[202:205], v185 offset:19456
	ds_read_b128 v[206:209], v185 offset:20480
	ds_read_b128 v[210:213], v185 offset:21504
	ds_read_b128 v[214:217], v185 offset:22528
	ds_read_b128 v[218:221], v185 offset:23552
	global_load_lds_dwordx4 v[222:223], off
	s_add_i32 m0, s68, 0x2000
	s_add_u32 s68, s26, 0x40000
	v_lshl_add_u64 v[224:225], s[26:27], 0, v[144:145]
	s_addc_u32 s69, s27, 0
	s_add_i32 s70, s50, s38
	global_load_lds_dwordx4 v[224:225], off
	v_lshl_add_u64 v[226:227], s[68:69], 0, v[148:149]
	s_mov_b32 m0, s70
	v_lshl_add_u64 v[228:229], s[36:37], 0, v[146:147]
	global_load_lds_dwordx4 v[226:227], off
	v_lshl_add_u64 v[226:227], s[68:69], 0, v[144:145]
	s_add_i32 m0, s70, 0x2000
	s_nop 0
	global_load_lds_dwordx4 v[226:227], off
	v_lshl_add_u64 v[226:227], s[36:37], 0, v[150:151]
	s_mov_b32 m0, s41
	s_nop 0
	global_load_lds_dwordx4 v[226:227], off
	s_mov_b32 m0, s42
	s_nop 0
	global_load_lds_dwordx4 v[228:229], off
	s_waitcnt vmcnt(8)
	s_waitcnt lgkmcnt(0)
	s_barrier
; #define PG8_STAGE(bufoff, gbase, voff) do { _Pragma("unroll") for (int _i = 0; _i < 2; ++_i) \
;         __builtin_amdgcn_global_load_lds((const unsigned*)((const char*)(gbase) + (voff)[_i]), (PG8_LAS unsigned*)(lds + (bufoff) + ldsw + _i * 8192), 16, 0, 0); } while (0)
; #define PG8_LDA(dst, b, h) do { _Pragma("unroll") for (int m = 0; m < 4; ++m) _Pragma("unroll") for (int k = 0; k < 2; ++k) dst[m][k] = *(const PG8_LAS bf16x8*)(lds + PG8_SA(b, h) + aoff + m * 2048 + k * 1024); } while (0)
; #define PG8_LDB(dst, b, h) do { _Pragma("unroll") for (int n = 0; n < 2; ++n) _Pragma("unroll") for (int k = 0; k < 2; ++k) dst[n][k] = *(const PG8_LAS bf16x8*)(lds + PG8_SB(b, h) + boff + n * 2048 + k * 1024); } while (0)
; #define PG8_MMA(ai, bj, At, Bt) do { __builtin_amdgcn_s_setprio(1); _Pragma("unroll") for (int m = 0; m < 4; ++m) _Pragma("unroll") for (int n = 0; n < 2; ++n) _Pragma("unroll") for (int k = 0; k < 2; ++k) \
;         acc[ai][bj][m][n] = __builtin_amdgcn_mfma_f32_16x16x32_bf16(Bt[n][k], At[m][k], acc[ai][bj][m][n], 0, 0, 0); __builtin_amdgcn_s_setprio(0); } while (0)
; #define PG8_WAIT_V(n) asm volatile("s_waitcnt vmcnt(" #n ")" ::: "memory")
; #define PG8_WAIT_L(n) asm volatile("s_waitcnt lgkmcnt(" #n ")" ::: "memory")
; #define PG8_BAR __builtin_amdgcn_s_barrier()
; #define PG8_SCHED __builtin_amdgcn_sched_barrier(0)
; template <class Epi, class Sched, bool ALIGN_EPI = false, bool SP2 = false>
; __device__ __forceinline__ void gemm_phase(PG8_LAS unsigned char* lds, const Gemm g, const Sched& S, const Epi& E) {
;     ...
;             PG8_WAIT_V(8); PG8_WAIT_L(0); PG8_BAR; PG8_MMA(1, 0, At, B0); PG8_MMA(1, 1, At, B1); PG8_BAR; PG8_SCHED;
;             PG8_LDB(B0, 1, 0); PG8_LDB(B1, 1, 1); PG8_SCHED; PG8_LDA(At, 1, 0); PG8_STAGE(PG8_SA(0, 1), a2 + hstep, voffA);
;             PG8_WAIT_V(8); PG8_WAIT_L(0); PG8_BAR; PG8_MMA(0, 0, At, B0); PG8_MMA(0, 1, At, B1); PG8_BAR; PG8_SCHED;
;             PG8_LDA(At, 1, 1); PG8_STAGE(PG8_SB(1, 0), b3, voffB); PG8_STAGE(PG8_SB(1, 1), b3 + hstep, voffB); PG8_STAGE(PG8_SA(1, 0), a3, voffA);
	s_setprio 1
	s_waitcnt lgkmcnt(0)
	v_mfma_f32_16x16x32_bf16 v[60:63], v[128:131], v[190:193], v[60:63]
	v_mfma_f32_16x16x32_bf16 v[56:59], v[136:139], v[190:193], v[56:59]
	v_mfma_f32_16x16x32_bf16 v[44:47], v[128:131], v[198:201], v[44:47]
	v_mfma_f32_16x16x32_bf16 v[40:43], v[136:139], v[198:201], v[40:43]
	v_mfma_f32_16x16x32_bf16 v[28:31], v[128:131], v[206:209], v[28:31]
	v_mfma_f32_16x16x32_bf16 v[24:27], v[136:139], v[206:209], v[24:27]
	v_mfma_f32_16x16x32_bf16 v[12:15], v[128:131], v[214:217], v[12:15]
	v_mfma_f32_16x16x32_bf16 v[8:11], v[136:139], v[214:217], v[8:11]
	v_mfma_f32_16x16x32_bf16 v[60:63], v[132:135], v[194:197], v[60:63]
	v_mfma_f32_16x16x32_bf16 v[56:59], v[140:143], v[194:197], v[56:59]
	v_mfma_f32_16x16x32_bf16 v[44:47], v[132:135], v[202:205], v[44:47]
	v_mfma_f32_16x16x32_bf16 v[40:43], v[140:143], v[202:205], v[40:43]
	v_mfma_f32_16x16x32_bf16 v[28:31], v[132:135], v[210:213], v[28:31]
	v_mfma_f32_16x16x32_bf16 v[24:27], v[140:143], v[210:213], v[24:27]
	v_mfma_f32_16x16x32_bf16 v[12:15], v[132:135], v[218:221], v[12:15]
	v_mfma_f32_16x16x32_bf16 v[8:11], v[140:143], v[218:221], v[8:11]
	s_setprio 0
	s_setprio 1
	v_mfma_f32_16x16x32_bf16 v[52:55], v[162:165], v[190:193], v[52:55]
	v_mfma_f32_16x16x32_bf16 v[48:51], v[170:173], v[190:193], v[48:51]
	v_mfma_f32_16x16x32_bf16 v[36:39], v[162:165], v[198:201], v[36:39]
	v_mfma_f32_16x16x32_bf16 v[32:35], v[170:173], v[198:201], v[32:35]
	v_mfma_f32_16x16x32_bf16 v[20:23], v[162:165], v[206:209], v[20:23]
	v_mfma_f32_16x16x32_bf16 v[16:19], v[170:173], v[206:209], v[16:19]
	v_mfma_f32_16x16x32_bf16 v[4:7], v[162:165], v[214:217], v[4:7]
	v_mfma_f32_16x16x32_bf16 v[0:3], v[170:173], v[214:217], v[0:3]
	v_mfma_f32_16x16x32_bf16 v[52:55], v[166:169], v[194:197], v[52:55]
	v_mfma_f32_16x16x32_bf16 v[48:51], v[174:177], v[194:197], v[48:51]
	v_mfma_f32_16x16x32_bf16 v[36:39], v[166:169], v[202:205], v[36:39]
	v_mfma_f32_16x16x32_bf16 v[32:35], v[174:177], v[202:205], v[32:35]
	v_mfma_f32_16x16x32_bf16 v[20:23], v[166:169], v[210:213], v[20:23]
	v_mfma_f32_16x16x32_bf16 v[16:19], v[174:177], v[210:213], v[16:19]
	v_mfma_f32_16x16x32_bf16 v[4:7], v[166:169], v[218:221], v[4:7]
	v_mfma_f32_16x16x32_bf16 v[0:3], v[174:177], v[218:221], v[0:3]
	s_setprio 0
	s_barrier
	s_add_i32 s68, 0, 0x18000
	s_add_i32 s69, 0, 0x1c000
	v_add_u32_e32 v140, s68, v181
	v_add_u32_e32 v174, s69, v181
	ds_read_b128 v[128:131], v140
	ds_read_b128 v[132:135], v140 offset:1024
	ds_read_b128 v[136:139], v140 offset:2048
	ds_read_b128 v[140:143], v140 offset:3072
	ds_read_b128 v[162:165], v174
	ds_read_b128 v[166:169], v174 offset:1024
	ds_read_b128 v[170:173], v174 offset:2048
	ds_read_b128 v[174:177], v174 offset:3072
	s_add_u32 s36, s36, 0x40000
	s_addc_u32 s37, s37, 0
	s_mov_b32 m0, s43
	v_lshl_add_u64 v[232:233], s[36:37], 0, v[150:151]
	ds_read_b128 v[190:193], v185 offset:32768
	ds_read_b128 v[194:197], v185 offset:33792
	ds_read_b128 v[198:201], v185 offset:34816
	ds_read_b128 v[202:205], v185 offset:35840
	ds_read_b128 v[206:209], v185 offset:36864
	ds_read_b128 v[210:213], v185 offset:37888
	ds_read_b128 v[214:217], v185 offset:38912
	ds_read_b128 v[218:221], v185 offset:39936
	global_load_lds_dwordx4 v[232:233], off
	v_lshl_add_u64 v[232:233], s[36:37], 0, v[146:147]
	s_mov_b32 m0, s44
	s_nop 0
	global_load_lds_dwordx4 v[232:233], off
	s_waitcnt vmcnt(8)
	s_waitcnt lgkmcnt(0)
	s_barrier
	s_setprio 1
	s_waitcnt lgkmcnt(0)
	v_mfma_f32_16x16x32_bf16 v[124:127], v[128:131], v[190:193], v[124:127]
	v_mfma_f32_16x16x32_bf16 v[120:123], v[136:139], v[190:193], v[120:123]
	v_mfma_f32_16x16x32_bf16 v[108:111], v[128:131], v[198:201], v[108:111]
	v_mfma_f32_16x16x32_bf16 v[104:107], v[136:139], v[198:201], v[104:107]
	v_mfma_f32_16x16x32_bf16 v[92:95], v[128:131], v[206:209], v[92:95]
	v_mfma_f32_16x16x32_bf16 v[88:91], v[136:139], v[206:209], v[88:91]
	v_mfma_f32_16x16x32_bf16 v[76:79], v[128:131], v[214:217], v[76:79]
	v_mfma_f32_16x16x32_bf16 v[72:75], v[136:139], v[214:217], v[72:75]
	v_mfma_f32_16x16x32_bf16 v[124:127], v[132:135], v[194:197], v[124:127]
	v_mfma_f32_16x16x32_bf16 v[120:123], v[140:143], v[194:197], v[120:123]
	v_mfma_f32_16x16x32_bf16 v[108:111], v[132:135], v[202:205], v[108:111]
	v_mfma_f32_16x16x32_bf16 v[104:107], v[140:143], v[202:205], v[104:107]
	v_mfma_f32_16x16x32_bf16 v[92:95], v[132:135], v[210:213], v[92:95]
	v_mfma_f32_16x16x32_bf16 v[88:91], v[140:143], v[210:213], v[88:91]
	v_mfma_f32_16x16x32_bf16 v[76:79], v[132:135], v[218:221], v[76:79]
	v_mfma_f32_16x16x32_bf16 v[72:75], v[140:143], v[218:221], v[72:75]
	s_setprio 0
	s_setprio 1
	v_mfma_f32_16x16x32_bf16 v[116:119], v[162:165], v[190:193], v[116:119]
	v_mfma_f32_16x16x32_bf16 v[112:115], v[170:173], v[190:193], v[112:115]
	v_mfma_f32_16x16x32_bf16 v[100:103], v[162:165], v[198:201], v[100:103]
	v_mfma_f32_16x16x32_bf16 v[96:99], v[170:173], v[198:201], v[96:99]
	v_mfma_f32_16x16x32_bf16 v[84:87], v[162:165], v[206:209], v[84:87]
	v_mfma_f32_16x16x32_bf16 v[80:83], v[170:173], v[206:209], v[80:83]
	v_mfma_f32_16x16x32_bf16 v[68:71], v[162:165], v[214:217], v[68:71]
	v_mfma_f32_16x16x32_bf16 v[64:67], v[170:173], v[214:217], v[64:67]
	v_mfma_f32_16x16x32_bf16 v[116:119], v[166:169], v[194:197], v[116:119]
	v_mfma_f32_16x16x32_bf16 v[112:115], v[174:177], v[194:197], v[112:115]
	v_mfma_f32_16x16x32_bf16 v[100:103], v[166:169], v[202:205], v[100:103]
	v_mfma_f32_16x16x32_bf16 v[96:99], v[174:177], v[202:205], v[96:99]
	v_mfma_f32_16x16x32_bf16 v[84:87], v[166:169], v[210:213], v[84:87]
	v_mfma_f32_16x16x32_bf16 v[80:83], v[174:177], v[210:213], v[80:83]
	v_mfma_f32_16x16x32_bf16 v[68:71], v[166:169], v[218:221], v[68:71]
	v_mfma_f32_16x16x32_bf16 v[64:67], v[174:177], v[218:221], v[64:67]
	s_setprio 0
	s_barrier
; #define PG8_STAGE(bufoff, gbase, voff) do { _Pragma("unroll") for (int _i = 0; _i < 2; ++_i) \
;         __builtin_amdgcn_global_load_lds((const unsigned*)((const char*)(gbase) + (voff)[_i]), (PG8_LAS unsigned*)(lds + (bufoff) + ldsw + _i * 8192), 16, 0, 0); } while (0)
; #define PG8_LDA(dst, b, h) do { _Pragma("unroll") for (int m = 0; m < 4; ++m) _Pragma("unroll") for (int k = 0; k < 2; ++k) dst[m][k] = *(const PG8_LAS bf16x8*)(lds + PG8_SA(b, h) + aoff + m * 2048 + k * 1024); } while (0)
; #define PG8_MMA(ai, bj, At, Bt) do { __builtin_amdgcn_s_setprio(1); _Pragma("unroll") for (int m = 0; m < 4; ++m) _Pragma("unroll") for (int n = 0; n < 2; ++n) _Pragma("unroll") for (int k = 0; k < 2; ++k) \
;         acc[ai][bj][m][n] = __builtin_amdgcn_mfma_f32_16x16x32_bf16(Bt[n][k], At[m][k], acc[ai][bj][m][n], 0, 0, 0); __builtin_amdgcn_s_setprio(0); } while (0)
; #define PG8_WAIT_V(n) asm volatile("s_waitcnt vmcnt(" #n ")" ::: "memory")
; #define PG8_WAIT_L(n) asm volatile("s_waitcnt lgkmcnt(" #n ")" ::: "memory")
; #define PG8_BAR __builtin_amdgcn_s_barrier()
; #define PG8_SCHED __builtin_amdgcn_sched_barrier(0)
; __device__ __forceinline__ void rows_rinv(const float* ssq, int row0, int fq, float (&ri)[2][4]) {
;     f32x4 p[2][4];
; #pragma unroll
;     for (int ai = 0; ai < 2; ++ai)
; #pragma unroll
;         for (int m = 0; m < 4; ++m) p[ai][m] = *(const f32x4*)(ssq + (size_t)(row0 + ai * HALF + m * 16) * 16 + 4 * fq);
; template <class Epi, class Sched, bool ALIGN_EPI = false, bool SP2 = false>
; __device__ __forceinline__ void gemm_phase(PG8_LAS unsigned char* lds, const Gemm g, const Sched& S, const Epi& E) {
;     ...
;             PG8_WAIT_V(8); PG8_WAIT_L(0); PG8_BAR; PG8_MMA(0, 0, At, B0); PG8_MMA(0, 1, At, B1); PG8_BAR; PG8_SCHED;
;             PG8_LDA(At, 1, 1); PG8_STAGE(PG8_SB(1, 0), b3, voffB); PG8_STAGE(PG8_SB(1, 1), b3 + hstep, voffB); PG8_STAGE(PG8_SA(1, 0), a3, voffA);
;             PG8_WAIT_V(8); PG8_WAIT_L(0); PG8_BAR; PG8_MMA(1, 0, At, B0); PG8_MMA(1, 1, At, B1); PG8_BAR; PG8_SCHED;
	s_add_i32 s36, s68, s38
	v_lshl_add_u64 v[222:223], v[222:223], 0, s[12:13]
	s_mov_b32 m0, s36
	ds_read_b128 v[190:193], v185 offset:49152
	ds_read_b128 v[194:197], v185 offset:50176
	ds_read_b128 v[198:201], v185 offset:51200
	ds_read_b128 v[202:205], v185 offset:52224
	ds_read_b128 v[206:209], v185 offset:53248
	ds_read_b128 v[210:213], v185 offset:54272
	ds_read_b128 v[214:217], v185 offset:55296
	ds_read_b128 v[218:221], v185 offset:56320
	global_load_lds_dwordx4 v[222:223], off
	s_add_i32 m0, s36, 0x2000
	s_add_u32 s26, s26, 0x40080
	v_lshl_add_u64 v[222:223], v[224:225], 0, s[12:13]
	s_addc_u32 s27, s27, 0
	s_add_i32 s36, s69, s38
	global_load_lds_dwordx4 v[222:223], off
	v_lshl_add_u64 v[222:223], s[26:27], 0, v[148:149]
	s_mov_b32 m0, s36
	s_nop 0
	global_load_lds_dwordx4 v[222:223], off
	v_lshl_add_u64 v[222:223], s[26:27], 0, v[144:145]
	s_add_i32 m0, s36, 0x2000
	s_nop 0
	global_load_lds_dwordx4 v[222:223], off
	v_lshl_add_u64 v[222:223], v[226:227], 0, s[12:13]
	s_mov_b32 m0, s46
	s_nop 0
	global_load_lds_dwordx4 v[222:223], off
	v_lshl_add_u64 v[222:223], v[228:229], 0, s[12:13]
	s_mov_b32 m0, s47
	s_nop 0
	global_load_lds_dwordx4 v[222:223], off
	s_waitcnt vmcnt(8)
	s_waitcnt lgkmcnt(0)
	s_barrier
	s_setprio 1
	s_waitcnt lgkmcnt(0)
	v_mfma_f32_16x16x32_bf16 v[60:63], v[128:131], v[190:193], v[60:63]
	v_mfma_f32_16x16x32_bf16 v[56:59], v[136:139], v[190:193], v[56:59]
	v_mfma_f32_16x16x32_bf16 v[44:47], v[128:131], v[198:201], v[44:47]
	v_mfma_f32_16x16x32_bf16 v[40:43], v[136:139], v[198:201], v[40:43]
	v_mfma_f32_16x16x32_bf16 v[28:31], v[128:131], v[206:209], v[28:31]
	v_mfma_f32_16x16x32_bf16 v[24:27], v[136:139], v[206:209], v[24:27]
	v_mfma_f32_16x16x32_bf16 v[12:15], v[128:131], v[214:217], v[12:15]
	v_mfma_f32_16x16x32_bf16 v[8:11], v[136:139], v[214:217], v[8:11]
	v_mfma_f32_16x16x32_bf16 v[60:63], v[132:135], v[194:197], v[60:63]
	v_mfma_f32_16x16x32_bf16 v[56:59], v[140:143], v[194:197], v[56:59]
	v_mfma_f32_16x16x32_bf16 v[44:47], v[132:135], v[202:205], v[44:47]
	v_mfma_f32_16x16x32_bf16 v[40:43], v[140:143], v[202:205], v[40:43]
	v_mfma_f32_16x16x32_bf16 v[28:31], v[132:135], v[210:213], v[28:31]
	v_mfma_f32_16x16x32_bf16 v[24:27], v[140:143], v[210:213], v[24:27]
	v_mfma_f32_16x16x32_bf16 v[12:15], v[132:135], v[218:221], v[12:15]
	v_mfma_f32_16x16x32_bf16 v[8:11], v[140:143], v[218:221], v[8:11]
	s_setprio 0
	s_setprio 1
	v_mfma_f32_16x16x32_bf16 v[52:55], v[162:165], v[190:193], v[52:55]
	v_mfma_f32_16x16x32_bf16 v[48:51], v[170:173], v[190:193], v[48:51]
	v_mfma_f32_16x16x32_bf16 v[36:39], v[162:165], v[198:201], v[36:39]
	v_mfma_f32_16x16x32_bf16 v[32:35], v[170:173], v[198:201], v[32:35]
	v_mfma_f32_16x16x32_bf16 v[20:23], v[162:165], v[206:209], v[20:23]
	v_mfma_f32_16x16x32_bf16 v[16:19], v[170:173], v[206:209], v[16:19]
	v_mfma_f32_16x16x32_bf16 v[4:7], v[162:165], v[214:217], v[4:7]
	v_mfma_f32_16x16x32_bf16 v[0:3], v[170:173], v[214:217], v[0:3]
	v_mfma_f32_16x16x32_bf16 v[52:55], v[166:169], v[194:197], v[52:55]
	v_mfma_f32_16x16x32_bf16 v[48:51], v[174:177], v[194:197], v[48:51]
	v_mfma_f32_16x16x32_bf16 v[36:39], v[166:169], v[202:205], v[36:39]
	v_mfma_f32_16x16x32_bf16 v[32:35], v[174:177], v[202:205], v[32:35]
	v_mfma_f32_16x16x32_bf16 v[20:23], v[166:169], v[210:213], v[20:23]
	v_mfma_f32_16x16x32_bf16 v[16:19], v[174:177], v[210:213], v[16:19]
	v_mfma_f32_16x16x32_bf16 v[4:7], v[166:169], v[218:221], v[4:7]
	v_mfma_f32_16x16x32_bf16 v[0:3], v[174:177], v[218:221], v[0:3]
	s_setprio 0
	s_barrier
	s_add_i32 s67, s67, 2
	s_add_u32 s4, s4, 0x100
	s_addc_u32 s5, s5, 0
	s_add_u32 s61, s61, 0x100
	s_addc_u32 s66, s66, 0
	s_cmp_gt_u32 s67, 13
	s_cbranch_scc0 .LBB0_895
	s_and_b64 vcc, exec, s[14:15]
	s_cbranch_vccz .LBB0_898
.LBB0_898:
	v_lshl_add_u32 v176, s0, 8, v179
	v_ashrrev_i32_e32 v177, 31, v176
	v_lshlrev_b64 v[128:129], 6, v[176:177]
	v_or_b32_e32 v174, 16, v176
	v_lshl_add_u64 v[128:129], v[152:153], 0, v[128:129]
	v_ashrrev_i32_e32 v175, 31, v174
	global_load_dwordx4 v[190:193], v[128:129], off
	v_lshlrev_b64 v[128:129], 6, v[174:175]
	v_lshl_add_u64 v[128:129], v[152:153], 0, v[128:129]
	global_load_dwordx4 v[194:197], v[128:129], off
	v_or_b32_e32 v172, 32, v176
	v_ashrrev_i32_e32 v173, 31, v172
	v_lshlrev_b64 v[128:129], 6, v[172:173]
	v_lshl_add_u64 v[128:129], v[152:153], 0, v[128:129]
	global_load_dwordx4 v[198:201], v[128:129], off
	v_and_b32_e32 v129, 64, v186
	v_xor_b32_e32 v128, 16, v186
	v_add_u32_e32 v129, 64, v129
	v_xor_b32_e32 v130, 32, v186
	v_or_b32_e32 v170, 48, v176
	v_add_u32_e32 v168, 0x80, v176
	v_add_u32_e32 v166, 0x90, v176
	v_add_u32_e32 v164, 0xa0, v176
	v_cmp_lt_i32_e32 vcc, v128, v129
	v_add_u32_e32 v162, 0xb0, v176
	v_ashrrev_i32_e32 v171, 31, v170
	v_ashrrev_i32_e32 v169, 31, v168
	v_ashrrev_i32_e32 v167, 31, v166
	v_ashrrev_i32_e32 v165, 31, v164
	v_cndmask_b32_e32 v138, v186, v128, vcc
	v_cmp_lt_i32_e32 vcc, v130, v129
	v_ashrrev_i32_e32 v163, 31, v162
	v_lshlrev_b64 v[128:129], 6, v[170:171]
	v_cndmask_b32_e32 v139, v186, v130, vcc
	v_lshlrev_b64 v[130:131], 6, v[168:169]
	v_lshlrev_b64 v[132:133], 6, v[166:167]
	v_lshlrev_b64 v[134:135], 6, v[164:165]
	v_lshlrev_b64 v[136:137], 6, v[162:163]
	v_lshl_add_u64 v[128:129], v[152:153], 0, v[128:129]
	v_lshl_add_u64 v[130:131], v[152:153], 0, v[130:131]
	v_lshl_add_u64 v[132:133], v[152:153], 0, v[132:133]
	v_lshl_add_u64 v[134:135], v[152:153], 0, v[134:135]
	v_lshlrev_b32_e32 v163, 2, v138
	v_lshlrev_b32_e32 v165, 2, v139
	v_lshl_add_u64 v[206:207], v[152:153], 0, v[136:137]
	global_load_dwordx4 v[202:205], v[128:129], off
	global_load_dwordx4 v[140:143], v[130:131], off
	global_load_dwordx4 v[136:139], v[132:133], off
	s_nop 0
	global_load_dwordx4 v[132:135], v[134:135], off
	s_nop 0
	global_load_dwordx4 v[128:131], v[206:207], off
	s_waitcnt vmcnt(0)
;     __device__ __forceinline__ void operator()(const f32x4 (&acc)[2][2][4][2], const Unit& u, int wr, int wc, int fr, int fq) const {
;     ...
;                 for (int n = 0; n < 2; ++n) { const f32x4 a = acc[ai][0][m][n] * ri[ai][m], b = acc[ai][1][m][n] * ri[ai][m]; f32x4 o;
; __device__ __forceinline__ void rows_rinv(const float* ssq, int row0, int fq, float (&ri)[2][4]) {
;     ...
;     for (int ai = 0; ai < 2; ++ai)
; #pragma unroll
;         for (int m = 0; m < 4; ++m) { float t = (p[ai][m][0] + p[ai][m][1]) + (p[ai][m][2] + p[ai][m][3]); t += __shfl_xor(t, 16); t += __shfl_xor(t, 32);
;             ri[ai][m] = 1.0f / sqrtf(t * (1.0f / 1024.0f) + 1e-6f); }
	v_mov_b32_e32 v206, v191
	v_mov_b32_e32 v207, v192
	v_mov_b32_e32 v191, v193
	v_pk_add_f32 v[190:191], v[206:207], v[190:191]
	v_mov_b32_e32 v192, v195
	v_mov_b32_e32 v193, v196
	v_mov_b32_e32 v195, v197
	v_add_f32_e32 v167, v190, v191
	v_pk_add_f32 v[190:191], v[192:193], v[194:195]
	ds_bpermute_b32 v169, v163, v167
	v_add_f32_e32 v171, v190, v191
	ds_bpermute_b32 v173, v163, v171
	v_mov_b32_e32 v196, v199
	v_mov_b32_e32 v197, v200
	s_waitcnt lgkmcnt(1)
	v_add_f32_e32 v167, v167, v169
	ds_bpermute_b32 v169, v165, v167
	s_waitcnt lgkmcnt(1)
	v_add_f32_e32 v171, v171, v173
	ds_bpermute_b32 v173, v165, v171
	v_mov_b32_e32 v199, v201
	v_pk_add_f32 v[190:191], v[196:197], v[198:199]
	s_waitcnt lgkmcnt(1)
	v_add_f32_e32 v167, v167, v169
	v_fmamk_f32 v167, v167, 0x3a800000, v187
	s_waitcnt lgkmcnt(0)
	v_add_f32_e32 v169, v171, v173
	v_mul_f32_e32 v171, 0x4f800000, v167
	v_cmp_gt_f32_e32 vcc, s51, v167
	v_fmamk_f32 v169, v169, 0x3a800000, v187
	v_cmp_gt_f32_e64 s[0:1], s51, v169
	v_cndmask_b32_e32 v167, v167, v171, vcc
	v_mul_f32_e32 v171, 0x4f800000, v169
	v_sqrt_f32_e32 v173, v167
	v_cndmask_b32_e64 v169, v169, v171, s[0:1]
	v_sqrt_f32_e32 v171, v169
	v_add_f32_e32 v175, v190, v191
	v_add_u32_e32 v178, -1, v173
	v_add_u32_e32 v180, 1, v173
	v_fma_f32 v189, -v178, v173, v167
	v_fma_f32 v190, -v180, v173, v167
	v_add_u32_e32 v191, -1, v171
	v_cmp_ge_f32_e64 s[4:5], 0, v189
	v_add_u32_e32 v192, 1, v171
	v_fma_f32 v189, -v192, v171, v169
	v_cndmask_b32_e64 v173, v173, v178, s[4:5]
	v_fma_f32 v178, -v191, v171, v169
	v_cmp_lt_f32_e64 s[4:5], 0, v190
	ds_bpermute_b32 v177, v163, v175
	s_nop 0
	v_cndmask_b32_e64 v173, v173, v180, s[4:5]
	v_cmp_ge_f32_e64 s[4:5], 0, v178
	v_mul_f32_e32 v178, 0x37800000, v173
	v_cndmask_b32_e32 v173, v173, v178, vcc
	v_cndmask_b32_e64 v171, v171, v191, s[4:5]
	v_cmp_lt_f32_e64 s[4:5], 0, v189
	v_cmp_class_f32_e32 vcc, v167, v188
	s_nop 0
	v_cndmask_b32_e64 v171, v171, v192, s[4:5]
	v_mul_f32_e32 v178, 0x37800000, v171
	v_cndmask_b32_e32 v167, v173, v167, vcc
	v_cndmask_b32_e64 v171, v171, v178, s[0:1]
	v_div_scale_f32 v173, s[0:1], v167, v167, 1.0
	v_cmp_class_f32_e32 vcc, v169, v188
	s_nop 1
	v_cndmask_b32_e32 v169, v171, v169, vcc
	v_rcp_f32_e32 v171, v173
	v_div_scale_f32 v180, vcc, 1.0, v167, 1.0
	v_div_scale_f32 v178, s[0:1], v169, v169, 1.0
	v_fma_f32 v190, -v173, v171, 1.0
	v_fmac_f32_e32 v171, v190, v171
	v_mul_f32_e32 v191, v180, v171
	v_fma_f32 v192, -v173, v191, v180
	v_fmac_f32_e32 v191, v192, v171
	v_fma_f32 v173, -v173, v191, v180
	v_div_fmas_f32 v171, v173, v171, v191
	v_div_fixup_f32 v180, v171, v167, 1.0
	s_waitcnt lgkmcnt(0)
	v_add_f32_e32 v167, v175, v177
	ds_bpermute_b32 v171, v165, v167
	v_rcp_f32_e32 v189, v178
	v_div_scale_f32 v173, vcc, 1.0, v169, 1.0
	v_mov_b32_e32 v191, v204
	s_waitcnt lgkmcnt(0)
	v_add_f32_e32 v167, v167, v171
	v_fmamk_f32 v167, v167, 0x3a800000, v187
	v_mul_f32_e32 v171, 0x4f800000, v167
	v_cmp_gt_f32_e64 s[0:1], s51, v167
	v_fma_f32 v190, -v178, v189, 1.0
	v_fmac_f32_e32 v189, v190, v189
	v_cndmask_b32_e64 v167, v167, v171, s[0:1]
	v_sqrt_f32_e32 v171, v167
	v_mov_b32_e32 v190, v203
	v_mov_b32_e32 v203, v205
	v_mul_f32_e32 v175, v173, v189
	v_pk_add_f32 v[190:191], v[190:191], v[202:203]
	v_fma_f32 v177, -v178, v175, v173
	v_add_f32_e32 v190, v190, v191
	v_fmac_f32_e32 v175, v177, v189
	v_add_u32_e32 v177, -1, v171
	ds_bpermute_b32 v191, v163, v190
	v_fma_f32 v173, -v178, v175, v173
	v_fma_f32 v178, -v177, v171, v167
	v_cmp_ge_f32_e64 s[4:5], 0, v178
	v_add_u32_e32 v178, 1, v171
	v_div_fmas_f32 v173, v173, v189, v175
	v_cndmask_b32_e64 v177, v171, v177, s[4:5]
	v_fma_f32 v171, -v178, v171, v167
	v_cmp_lt_f32_e64 s[4:5], 0, v171
	v_pk_mul_f32 v[126:127], v[126:127], v[180:181] op_sel_hi:[1,0]
	v_pk_mul_f32 v[116:117], v[116:117], v[180:181] op_sel_hi:[1,0]
	v_cndmask_b32_e64 v171, v177, v178, s[4:5]
	v_div_fixup_f32 v178, v173, v169, 1.0
	s_waitcnt lgkmcnt(0)
	v_add_f32_e32 v173, v190, v191
	v_mul_f32_e32 v177, 0x37800000, v171
	ds_bpermute_b32 v175, v165, v173
	v_cndmask_b32_e64 v171, v171, v177, s[0:1]
	v_cmp_class_f32_e64 s[0:1], v167, v188
	v_mov_b32_e32 v191, v142
	v_pk_mul_f32 v[118:119], v[118:119], v[180:181] op_sel_hi:[1,0]
	v_cndmask_b32_e64 v167, v171, v167, s[0:1]
	v_div_scale_f32 v171, s[0:1], v167, v167, 1.0
	v_rcp_f32_e32 v177, v171
	s_waitcnt lgkmcnt(0)
	v_add_f32_e32 v173, v173, v175
	v_fmamk_f32 v173, v173, 0x3a800000, v187
	v_mul_f32_e32 v175, 0x4f800000, v173
	v_cmp_gt_f32_e64 s[0:1], s51, v173
	v_fma_f32 v169, -v171, v177, 1.0
	v_fmac_f32_e32 v177, v169, v177
	v_cndmask_b32_e64 v173, v173, v175, s[0:1]
	v_div_scale_f32 v169, vcc, 1.0, v167, 1.0
	v_sqrt_f32_e32 v175, v173
	v_mul_f32_e32 v189, v169, v177
	v_fma_f32 v190, -v171, v189, v169
	v_fmac_f32_e32 v189, v190, v177
	v_fma_f32 v169, -v171, v189, v169
	v_add_u32_e32 v171, -1, v175
	v_fma_f32 v190, -v171, v175, v173
	v_cmp_ge_f32_e64 s[4:5], 0, v190
	v_add_u32_e32 v190, 1, v175
	v_pk_mul_f32 v[120:121], v[120:121], v[180:181] op_sel_hi:[1,0]
	v_cndmask_b32_e64 v171, v175, v171, s[4:5]
	v_fma_f32 v175, -v190, v175, v173
	v_cmp_lt_f32_e64 s[4:5], 0, v175
	v_pk_mul_f32 v[122:123], v[122:123], v[180:181] op_sel_hi:[1,0]
	v_pk_mul_f32 v[112:113], v[112:113], v[180:181] op_sel_hi:[1,0]
	v_cndmask_b32_e64 v171, v171, v190, s[4:5]
	v_mov_b32_e32 v190, v141
	v_mov_b32_e32 v141, v143
	v_pk_add_f32 v[140:141], v[190:191], v[140:141]
	v_mul_f32_e32 v175, 0x37800000, v171
	v_add_f32_e32 v141, v140, v141
	ds_bpermute_b32 v142, v163, v141
	v_cndmask_b32_e64 v171, v171, v175, s[0:1]
	v_cmp_class_f32_e64 s[0:1], v173, v188
	v_div_fmas_f32 v140, v169, v177, v189
	v_div_fixup_f32 v140, v140, v167, 1.0
	s_waitcnt lgkmcnt(0)
; __device__ __forceinline__ void rows_rinv(const float* ssq, int row0, int fq, float (&ri)[2][4]) {
;     ...
;     for (int ai = 0; ai < 2; ++ai)
; #pragma unroll
;         for (int m = 0; m < 4; ++m) { float t = (p[ai][m][0] + p[ai][m][1]) + (p[ai][m][2] + p[ai][m][3]); t += __shfl_xor(t, 16); t += __shfl_xor(t, 32);
;             ri[ai][m] = 1.0f / sqrtf(t * (1.0f / 1024.0f) + 1e-6f); }
	v_add_f32_e32 v141, v141, v142
	ds_bpermute_b32 v142, v165, v141
	v_cndmask_b32_e64 v171, v171, v173, s[0:1]
	v_div_scale_f32 v173, s[0:1], v171, v171, 1.0
	v_rcp_f32_e32 v175, v173
	s_waitcnt lgkmcnt(0)
	v_add_f32_e32 v141, v141, v142
	v_fmamk_f32 v141, v141, 0x3a800000, v187
	v_mul_f32_e32 v142, 0x4f800000, v141
	v_cmp_gt_f32_e64 s[0:1], s51, v141
	v_fma_f32 v143, -v173, v175, 1.0
	v_fmac_f32_e32 v175, v143, v175
	v_cndmask_b32_e64 v141, v141, v142, s[0:1]
	v_div_scale_f32 v143, vcc, 1.0, v171, 1.0
	v_sqrt_f32_e32 v142, v141
	v_mul_f32_e32 v167, v143, v175
	v_fma_f32 v169, -v173, v167, v143
	v_fmac_f32_e32 v167, v169, v175
	v_fma_f32 v169, -v173, v167, v143
	v_add_u32_e32 v143, -1, v142
	v_fma_f32 v173, -v143, v142, v141
	v_cmp_ge_f32_e64 s[4:5], 0, v173
	v_add_u32_e32 v173, 1, v142
	v_pk_mul_f32 v[114:115], v[114:115], v[180:181] op_sel_hi:[1,0]
	v_cndmask_b32_e64 v143, v142, v143, s[4:5]
	v_fma_f32 v142, -v173, v142, v141
	v_cmp_lt_f32_e64 s[4:5], 0, v142
	v_pk_mul_f32 v[108:109], v[108:109], v[178:179] op_sel_hi:[1,0]
	v_pk_mul_f32 v[110:111], v[110:111], v[178:179] op_sel_hi:[1,0]
	v_cndmask_b32_e64 v142, v143, v173, s[4:5]
	v_mul_f32_e32 v143, 0x37800000, v142
	v_cndmask_b32_e64 v142, v142, v143, s[0:1]
	v_cmp_class_f32_e64 s[0:1], v141, v188
	v_mov_b32_e32 v143, v138
	v_pk_mul_f32 v[100:101], v[100:101], v[178:179] op_sel_hi:[1,0]
	v_cndmask_b32_e64 v141, v142, v141, s[0:1]
	v_mov_b32_e32 v142, v137
	v_mov_b32_e32 v137, v139
	v_pk_add_f32 v[136:137], v[142:143], v[136:137]
	v_div_scale_f32 v173, s[0:1], v141, v141, 1.0
	v_add_f32_e32 v137, v136, v137
	ds_bpermute_b32 v138, v163, v137
	v_rcp_f32_e32 v177, v173
	v_div_fmas_f32 v136, v169, v175, v167
	v_pk_mul_f32 v[102:103], v[102:103], v[178:179] op_sel_hi:[1,0]
	v_pk_mul_f32 v[104:105], v[104:105], v[178:179] op_sel_hi:[1,0]
	s_waitcnt lgkmcnt(0)
	v_add_f32_e32 v137, v137, v138
	ds_bpermute_b32 v138, v165, v137
	v_fma_f32 v139, -v173, v177, 1.0
	v_fmac_f32_e32 v177, v139, v177
	v_div_scale_f32 v139, vcc, 1.0, v141, 1.0
	s_waitcnt lgkmcnt(0)
	v_add_f32_e32 v137, v137, v138
	v_fmamk_f32 v137, v137, 0x3a800000, v187
	v_mul_f32_e32 v138, 0x4f800000, v137
	v_cmp_gt_f32_e64 s[0:1], s51, v137
	v_mul_f32_e32 v142, v139, v177
	v_fma_f32 v143, -v173, v142, v139
	v_cndmask_b32_e64 v137, v137, v138, s[0:1]
	v_sqrt_f32_e32 v138, v137
	v_fmac_f32_e32 v142, v143, v177
	v_fma_f32 v143, -v173, v142, v139
	v_pk_mul_f32 v[106:107], v[106:107], v[178:179] op_sel_hi:[1,0]
	v_add_u32_e32 v139, -1, v138
	v_fma_f32 v167, -v139, v138, v137
	v_cmp_ge_f32_e64 s[4:5], 0, v167
	v_add_u32_e32 v167, 1, v138
	v_pk_mul_f32 v[96:97], v[96:97], v[178:179] op_sel_hi:[1,0]
	v_cndmask_b32_e64 v139, v138, v139, s[4:5]
	v_fma_f32 v138, -v167, v138, v137
	v_cmp_lt_f32_e64 s[4:5], 0, v138
	v_pk_mul_f32 v[98:99], v[98:99], v[178:179] op_sel_hi:[1,0]
	v_div_fixup_f32 v136, v136, v171, 1.0
	v_cndmask_b32_e64 v138, v139, v167, s[4:5]
	v_mul_f32_e32 v139, 0x37800000, v138
	v_cndmask_b32_e64 v138, v138, v139, s[0:1]
	v_cmp_class_f32_e64 s[0:1], v137, v188
	v_mov_b32_e32 v139, v134
	v_div_fmas_f32 v134, v143, v177, v142
	v_cndmask_b32_e64 v137, v138, v137, s[0:1]
	v_mov_b32_e32 v138, v133
	v_mov_b32_e32 v133, v135
	v_pk_add_f32 v[132:133], v[138:139], v[132:133]
	v_div_scale_f32 v167, s[0:1], v137, v137, 1.0
	v_add_f32_e32 v132, v132, v133
	ds_bpermute_b32 v133, v163, v132
	v_rcp_f32_e32 v169, v167
	v_div_fixup_f32 v134, v134, v141, 1.0
	s_waitcnt lgkmcnt(0)
	v_add_f32_e32 v132, v132, v133
	ds_bpermute_b32 v133, v165, v132
	v_fma_f32 v135, -v167, v169, 1.0
	v_fmac_f32_e32 v169, v135, v169
	v_div_scale_f32 v135, vcc, 1.0, v137, 1.0
	s_waitcnt lgkmcnt(0)
	v_add_f32_e32 v132, v132, v133
	v_fmamk_f32 v132, v132, 0x3a800000, v187
	v_mul_f32_e32 v133, 0x4f800000, v132
	v_cmp_gt_f32_e64 s[0:1], s51, v132
	v_mul_f32_e32 v138, v135, v169
	v_fma_f32 v139, -v167, v138, v135
	v_cndmask_b32_e64 v132, v132, v133, s[0:1]
	v_sqrt_f32_e32 v133, v132
	v_fmac_f32_e32 v138, v139, v169
	v_fma_f32 v135, -v167, v138, v135
	v_add_u32_e32 v139, -1, v133
	v_fma_f32 v141, -v139, v133, v132
	v_cmp_ge_f32_e64 s[4:5], 0, v141
	v_add_u32_e32 v141, 1, v133
	s_nop 0
	v_cndmask_b32_e64 v139, v133, v139, s[4:5]
	v_fma_f32 v133, -v141, v133, v132
	v_cmp_lt_f32_e64 s[4:5], 0, v133
	s_nop 1
	v_cndmask_b32_e64 v133, v139, v141, s[4:5]
	v_mul_f32_e32 v139, 0x37800000, v133
	v_cndmask_b32_e64 v133, v133, v139, s[0:1]
	v_cmp_class_f32_e64 s[0:1], v132, v188
	s_nop 1
	v_cndmask_b32_e64 v139, v133, v132, s[0:1]
	v_mov_b32_e32 v132, v129
	v_mov_b32_e32 v133, v130
	v_mov_b32_e32 v129, v131
	v_pk_add_f32 v[128:129], v[132:133], v[128:129]
	v_div_scale_f32 v141, s[0:1], v139, v139, 1.0
	v_add_f32_e32 v128, v128, v129
	ds_bpermute_b32 v129, v163, v128
	v_rcp_f32_e32 v142, v141
	v_div_fmas_f32 v130, v135, v169, v138
	v_div_fixup_f32 v132, v130, v137, 1.0
	v_lshl_or_b32 v138, s53, 7, v182
	s_waitcnt lgkmcnt(0)
	v_add_f32_e32 v128, v128, v129
	ds_bpermute_b32 v129, v165, v128
	v_fma_f32 v130, -v141, v142, 1.0
	v_fmac_f32_e32 v142, v130, v142
	v_div_scale_f32 v130, vcc, 1.0, v139, 1.0
	s_waitcnt lgkmcnt(0)
; __device__ __forceinline__ u32x2 pack4(f32x4 v) { u32x2 w; w.x = cvt_pk_bf16(v[0], v[1]); w.y = cvt_pk_bf16(v[2], v[3]); return w; }
;     __device__ __forceinline__ void operator()(const f32x4 (&acc)[2][2][4][2], const Unit& u, int wr, int wc, int fr, int fq) const {
;     ...
;             for (int m = 0; m < 4; ++m) { const int row = row0 + ai * HALF + m * 16; bf16_t* rowp = (bf16_t*)(ws + WS_ACT) + (size_t)row * DFF + col0; u32x4e w;
; #pragma unroll
;                 for (int n = 0; n < 2; ++n) { const f32x4 a = acc[ai][0][m][n] * ri[ai][m], b = acc[ai][1][m][n] * ri[ai][m]; f32x4 o;
; #pragma unroll
;                     for (int i = 0; i < 4; ++i) o[i] = a[i] * __builtin_amdgcn_rcpf(1.0f + __builtin_amdgcn_exp2f(-a[i])) * b[i];
;                     const u32x2 p = pack4(o); w[2 * n] = p.x; w[2 * n + 1] = p.y; }
;                 *(u32x4e*)rowp = w; }
; __device__ __forceinline__ void rows_rinv(const float* ssq, int row0, int fq, float (&ri)[2][4]) {
;     ...
;         for (int m = 0; m < 4; ++m) { float t = (p[ai][m][0] + p[ai][m][1]) + (p[ai][m][2] + p[ai][m][3]); t += __shfl_xor(t, 16); t += __shfl_xor(t, 32);
;             ri[ai][m] = 1.0f / sqrtf(t * (1.0f / 1024.0f) + 1e-6f); }
	v_add_f32_e32 v128, v128, v129
	v_fmamk_f32 v128, v128, 0x3a800000, v187
	v_mul_f32_e32 v129, 0x4f800000, v128
	v_cmp_gt_f32_e64 s[0:1], s51, v128
	v_mul_f32_e32 v131, v130, v142
	v_fma_f32 v133, -v141, v131, v130
	v_cndmask_b32_e64 v128, v128, v129, s[0:1]
	v_sqrt_f32_e32 v129, v128
	v_fmac_f32_e32 v131, v133, v142
	v_fma_f32 v130, -v141, v131, v130
	v_div_fmas_f32 v130, v130, v142, v131
	v_add_u32_e32 v133, -1, v129
	v_fma_f32 v135, -v133, v129, v128
	v_cmp_ge_f32_e64 s[4:5], 0, v135
	v_add_u32_e32 v135, 1, v129
	v_pk_mul_f32 v[142:143], v[124:125], v[180:181] op_sel_hi:[1,0]
	v_cndmask_b32_e64 v133, v129, v133, s[4:5]
	v_fma_f32 v129, -v135, v129, v128
	v_cmp_lt_f32_e64 s[4:5], 0, v129
	v_div_fixup_f32 v130, v130, v139, 1.0
	v_ashrrev_i32_e32 v139, 31, v138
	v_cndmask_b32_e64 v129, v133, v135, s[4:5]
	v_mul_f32_e32 v133, 0x37800000, v129
	v_cndmask_b32_e64 v129, v129, v133, s[0:1]
	v_cmp_class_f32_e64 s[0:1], v128, v188
	v_mov_b64_e32 v[124:125], s[16:17]
	v_pk_mul_f32 v[92:93], v[92:93], v[140:141] op_sel_hi:[1,0]
	v_cndmask_b32_e64 v128, v129, v128, s[0:1]
	v_div_scale_f32 v129, s[0:1], v128, v128, 1.0
	v_rcp_f32_e32 v133, v129
	v_mad_i64_i32 v[176:177], s[0:1], v176, s52, v[124:125]
	v_pk_mul_f32 v[94:95], v[94:95], v[140:141] op_sel_hi:[1,0]
	v_fma_f32 v131, -v129, v133, 1.0
	v_fmac_f32_e32 v133, v131, v133
	v_div_scale_f32 v131, vcc, 1.0, v128, 1.0
	v_mul_f32_e32 v135, v131, v133
	v_fma_f32 v137, -v129, v135, v131
	v_fmac_f32_e32 v135, v137, v133
	v_fma_f32 v129, -v129, v135, v131
	v_div_fmas_f32 v129, v129, v133, v135
	v_div_fixup_f32 v128, v129, v128, 1.0
	v_exp_f32_e64 v129, -v142
	v_exp_f32_e64 v131, -v143
	v_exp_f32_e64 v133, -v127
	v_pk_mul_f32 v[84:85], v[84:85], v[140:141] op_sel_hi:[1,0]
	v_add_f32_e32 v129, 1.0, v129
	v_rcp_f32_e32 v190, v129
	v_exp_f32_e64 v129, -v126
	v_add_f32_e32 v131, 1.0, v131
	v_rcp_f32_e32 v191, v131
	v_pk_mul_f32 v[86:87], v[86:87], v[140:141] op_sel_hi:[1,0]
	v_add_f32_e32 v129, 1.0, v129
	v_rcp_f32_e32 v192, v129
	v_add_f32_e32 v129, 1.0, v133
	v_rcp_f32_e32 v193, v129
	v_pk_mul_f32 v[142:143], v[142:143], v[190:191]
	v_exp_f32_e64 v129, -v120
	v_pk_mul_f32 v[116:117], v[116:117], v[142:143]
	v_pk_mul_f32 v[126:127], v[126:127], v[192:193]
	v_cvt_pk_bf16_f32 v116, v116, v117
	v_pk_mul_f32 v[118:119], v[118:119], v[126:127]
	v_exp_f32_e64 v126, -v122
	v_cvt_pk_bf16_f32 v117, v118, v119
	v_exp_f32_e64 v119, -v121
	v_exp_f32_e64 v127, -v123
	v_add_f32_e32 v118, 1.0, v129
	v_rcp_f32_e32 v118, v118
	v_add_f32_e32 v119, 1.0, v119
	v_rcp_f32_e32 v119, v119
	v_add_f32_e32 v126, 1.0, v126
	v_add_f32_e32 v127, 1.0, v127
	v_rcp_f32_e32 v126, v126
	v_rcp_f32_e32 v127, v127
	v_pk_mul_f32 v[118:119], v[120:121], v[118:119]
	v_exp_f32_e64 v120, -v108
	v_pk_mul_f32 v[112:113], v[112:113], v[118:119]
	v_pk_mul_f32 v[118:119], v[122:123], v[126:127]
	v_pk_mul_f32 v[88:89], v[88:89], v[140:141] op_sel_hi:[1,0]
	v_pk_mul_f32 v[114:115], v[114:115], v[118:119]
	v_cvt_pk_bf16_f32 v118, v112, v113
	v_lshlrev_b64 v[112:113], 1, v[138:139]
	v_cvt_pk_bf16_f32 v119, v114, v115
	v_lshl_add_u64 v[114:115], v[176:177], 0, v[112:113]
	global_store_dwordx4 v[114:115], v[116:119], off
	v_mad_i64_i32 v[114:115], s[0:1], v174, s52, v[124:125]
	s_nop 0
	v_exp_f32_e64 v117, -v109
	v_exp_f32_e64 v118, -v110
	v_exp_f32_e64 v119, -v111
	v_add_f32_e32 v116, 1.0, v120
	v_add_f32_e32 v117, 1.0, v117
	v_rcp_f32_e32 v116, v116
	v_rcp_f32_e32 v117, v117
	v_add_f32_e32 v118, 1.0, v118
	v_add_f32_e32 v119, 1.0, v119
	v_rcp_f32_e32 v118, v118
	v_rcp_f32_e32 v119, v119
	v_pk_mul_f32 v[108:109], v[108:109], v[116:117]
	v_pk_mul_f32 v[90:91], v[90:91], v[140:141] op_sel_hi:[1,0]
	v_pk_mul_f32 v[100:101], v[100:101], v[108:109]
	v_pk_mul_f32 v[108:109], v[110:111], v[118:119]
	v_exp_f32_e64 v110, -v104
	v_pk_mul_f32 v[102:103], v[102:103], v[108:109]
	v_cvt_pk_bf16_f32 v100, v100, v101
	v_cvt_pk_bf16_f32 v101, v102, v103
	v_exp_f32_e64 v103, -v105
	v_exp_f32_e64 v108, -v106
	v_exp_f32_e64 v109, -v107
	v_add_f32_e32 v102, 1.0, v110
	v_add_f32_e32 v103, 1.0, v103
	v_rcp_f32_e32 v102, v102
	v_rcp_f32_e32 v103, v103
	v_add_f32_e32 v108, 1.0, v108
	v_add_f32_e32 v109, 1.0, v109
	v_rcp_f32_e32 v108, v108
	v_rcp_f32_e32 v109, v109
	v_pk_mul_f32 v[102:103], v[104:105], v[102:103]
	v_pk_mul_f32 v[80:81], v[80:81], v[140:141] op_sel_hi:[1,0]
	v_pk_mul_f32 v[96:97], v[96:97], v[102:103]
	v_pk_mul_f32 v[102:103], v[106:107], v[108:109]
	v_pk_mul_f32 v[82:83], v[82:83], v[140:141] op_sel_hi:[1,0]
	v_pk_mul_f32 v[98:99], v[98:99], v[102:103]
	v_cvt_pk_bf16_f32 v102, v96, v97
	v_cvt_pk_bf16_f32 v103, v98, v99
	v_lshl_add_u64 v[96:97], v[114:115], 0, v[112:113]
	v_exp_f32_e64 v98, -v92
	v_exp_f32_e64 v99, -v93
	global_store_dwordx4 v[96:97], v[100:103], off
	v_mad_i64_i32 v[96:97], s[0:1], v172, s52, v[124:125]
	s_nop 0
	v_exp_f32_e64 v100, -v94
	v_exp_f32_e64 v101, -v95
	v_add_f32_e32 v98, 1.0, v98
	v_add_f32_e32 v99, 1.0, v99
	v_rcp_f32_e32 v98, v98
	v_rcp_f32_e32 v99, v99
	v_add_f32_e32 v100, 1.0, v100
	v_add_f32_e32 v101, 1.0, v101
	v_rcp_f32_e32 v100, v100
	v_rcp_f32_e32 v101, v101
	v_pk_mul_f32 v[92:93], v[92:93], v[98:99]
	v_pk_mul_f32 v[76:77], v[76:77], v[136:137] op_sel_hi:[1,0]
	v_pk_mul_f32 v[84:85], v[84:85], v[92:93]
	v_pk_mul_f32 v[92:93], v[94:95], v[100:101]
	v_exp_f32_e64 v94, -v88
	v_pk_mul_f32 v[86:87], v[86:87], v[92:93]
	v_cvt_pk_bf16_f32 v84, v84, v85
	v_cvt_pk_bf16_f32 v85, v86, v87
	v_exp_f32_e64 v87, -v89
	v_exp_f32_e64 v92, -v90
	v_exp_f32_e64 v93, -v91
	v_add_f32_e32 v86, 1.0, v94
	v_add_f32_e32 v87, 1.0, v87
	v_rcp_f32_e32 v86, v86
	v_rcp_f32_e32 v87, v87
	v_add_f32_e32 v92, 1.0, v92
	v_add_f32_e32 v93, 1.0, v93
	v_rcp_f32_e32 v92, v92
; __device__ __forceinline__ u32x2 pack4(f32x4 v) { u32x2 w; w.x = cvt_pk_bf16(v[0], v[1]); w.y = cvt_pk_bf16(v[2], v[3]); return w; }
;     __device__ __forceinline__ void operator()(const f32x4 (&acc)[2][2][4][2], const Unit& u, int wr, int wc, int fr, int fq) const {
;     ...
;             for (int m = 0; m < 4; ++m) { const int row = row0 + ai * HALF + m * 16; bf16_t* rowp = (bf16_t*)(ws + WS_ACT) + (size_t)row * DFF + col0; u32x4e w;
; #pragma unroll
;                 for (int n = 0; n < 2; ++n) { const f32x4 a = acc[ai][0][m][n] * ri[ai][m], b = acc[ai][1][m][n] * ri[ai][m]; f32x4 o;
; #pragma unroll
;                     for (int i = 0; i < 4; ++i) o[i] = a[i] * __builtin_amdgcn_rcpf(1.0f + __builtin_amdgcn_exp2f(-a[i])) * b[i];
;                     const u32x2 p = pack4(o); w[2 * n] = p.x; w[2 * n + 1] = p.y; }
;                 *(u32x4e*)rowp = w; }
	v_rcp_f32_e32 v93, v93
	v_pk_mul_f32 v[86:87], v[88:89], v[86:87]
	v_pk_mul_f32 v[78:79], v[78:79], v[136:137] op_sel_hi:[1,0]
	v_pk_mul_f32 v[80:81], v[80:81], v[86:87]
	v_pk_mul_f32 v[86:87], v[90:91], v[92:93]
	v_pk_mul_f32 v[68:69], v[68:69], v[136:137] op_sel_hi:[1,0]
	v_pk_mul_f32 v[82:83], v[82:83], v[86:87]
	v_cvt_pk_bf16_f32 v86, v80, v81
	v_cvt_pk_bf16_f32 v87, v82, v83
	v_lshl_add_u64 v[80:81], v[96:97], 0, v[112:113]
	v_exp_f32_e64 v82, -v76
	v_exp_f32_e64 v83, -v77
	global_store_dwordx4 v[80:81], v[84:87], off
	v_pk_mul_f32 v[70:71], v[70:71], v[136:137] op_sel_hi:[1,0]
	v_add_f32_e32 v82, 1.0, v82
	v_exp_f32_e64 v84, -v78
	v_exp_f32_e64 v85, -v79
	v_add_f32_e32 v83, 1.0, v83
	v_rcp_f32_e32 v82, v82
	v_rcp_f32_e32 v83, v83
	v_add_f32_e32 v84, 1.0, v84
	v_add_f32_e32 v85, 1.0, v85
	v_rcp_f32_e32 v84, v84
	v_rcp_f32_e32 v85, v85
	v_pk_mul_f32 v[76:77], v[76:77], v[82:83]
	v_pk_mul_f32 v[72:73], v[72:73], v[136:137] op_sel_hi:[1,0]
	v_pk_mul_f32 v[68:69], v[68:69], v[76:77]
	v_pk_mul_f32 v[76:77], v[78:79], v[84:85]
	v_exp_f32_e64 v78, -v72
	v_pk_mul_f32 v[70:71], v[70:71], v[76:77]
	v_cvt_pk_bf16_f32 v68, v68, v69
	v_cvt_pk_bf16_f32 v69, v70, v71
	v_exp_f32_e64 v71, -v73
	v_pk_mul_f32 v[74:75], v[74:75], v[136:137] op_sel_hi:[1,0]
	v_add_f32_e32 v70, 1.0, v78
	v_exp_f32_e64 v76, -v74
	v_exp_f32_e64 v77, -v75
	v_add_f32_e32 v71, 1.0, v71
	v_rcp_f32_e32 v70, v70
	v_rcp_f32_e32 v71, v71
	v_add_f32_e32 v76, 1.0, v76
	v_add_f32_e32 v77, 1.0, v77
	v_rcp_f32_e32 v76, v76
	v_rcp_f32_e32 v77, v77
	v_pk_mul_f32 v[70:71], v[72:73], v[70:71]
	v_pk_mul_f32 v[64:65], v[64:65], v[136:137] op_sel_hi:[1,0]
	v_pk_mul_f32 v[66:67], v[66:67], v[136:137] op_sel_hi:[1,0]
	v_pk_mul_f32 v[64:65], v[64:65], v[70:71]
	v_pk_mul_f32 v[70:71], v[74:75], v[76:77]
	v_mad_i64_i32 v[80:81], s[0:1], v170, s52, v[124:125]
	v_pk_mul_f32 v[66:67], v[66:67], v[70:71]
	v_pk_mul_f32 v[60:61], v[60:61], v[134:135] op_sel_hi:[1,0]
	v_cvt_pk_bf16_f32 v70, v64, v65
	v_cvt_pk_bf16_f32 v71, v66, v67
	v_lshl_add_u64 v[64:65], v[80:81], 0, v[112:113]
	v_exp_f32_e64 v66, -v60
	v_exp_f32_e64 v67, -v61
	v_pk_mul_f32 v[62:63], v[62:63], v[134:135] op_sel_hi:[1,0]
	global_store_dwordx4 v[64:65], v[68:71], off
	v_add_f32_e32 v66, 1.0, v66
	v_add_f32_e32 v67, 1.0, v67
	v_exp_f32_e64 v68, -v62
	v_exp_f32_e64 v69, -v63
	v_rcp_f32_e32 v66, v66
	v_rcp_f32_e32 v67, v67
	v_add_f32_e32 v68, 1.0, v68
	v_add_f32_e32 v69, 1.0, v69
	v_rcp_f32_e32 v68, v68
	v_rcp_f32_e32 v69, v69
	v_pk_mul_f32 v[60:61], v[60:61], v[66:67]
	v_pk_mul_f32 v[52:53], v[52:53], v[134:135] op_sel_hi:[1,0]
	v_pk_mul_f32 v[54:55], v[54:55], v[134:135] op_sel_hi:[1,0]
	v_pk_mul_f32 v[52:53], v[52:53], v[60:61]
	v_pk_mul_f32 v[60:61], v[62:63], v[68:69]
	v_pk_mul_f32 v[56:57], v[56:57], v[134:135] op_sel_hi:[1,0]
	v_pk_mul_f32 v[54:55], v[54:55], v[60:61]
	v_exp_f32_e64 v62, -v56
	v_cvt_pk_bf16_f32 v52, v52, v53
	v_cvt_pk_bf16_f32 v53, v54, v55
	v_exp_f32_e64 v55, -v57
	v_pk_mul_f32 v[58:59], v[58:59], v[134:135] op_sel_hi:[1,0]
	v_add_f32_e32 v54, 1.0, v62
	v_exp_f32_e64 v60, -v58
	v_exp_f32_e64 v61, -v59
	v_add_f32_e32 v55, 1.0, v55
	v_rcp_f32_e32 v54, v54
	v_rcp_f32_e32 v55, v55
	v_add_f32_e32 v60, 1.0, v60
	v_add_f32_e32 v61, 1.0, v61
	v_rcp_f32_e32 v60, v60
	v_rcp_f32_e32 v61, v61
	v_pk_mul_f32 v[54:55], v[56:57], v[54:55]
	v_pk_mul_f32 v[48:49], v[48:49], v[134:135] op_sel_hi:[1,0]
	v_pk_mul_f32 v[50:51], v[50:51], v[134:135] op_sel_hi:[1,0]
	v_pk_mul_f32 v[48:49], v[48:49], v[54:55]
	v_pk_mul_f32 v[54:55], v[58:59], v[60:61]
	v_mad_i64_i32 v[64:65], s[0:1], v168, s52, v[124:125]
	v_pk_mul_f32 v[50:51], v[50:51], v[54:55]
	v_pk_mul_f32 v[44:45], v[44:45], v[132:133] op_sel_hi:[1,0]
	v_cvt_pk_bf16_f32 v54, v48, v49
	v_cvt_pk_bf16_f32 v55, v50, v51
	v_lshl_add_u64 v[48:49], v[64:65], 0, v[112:113]
	v_exp_f32_e64 v50, -v44
	v_exp_f32_e64 v51, -v45
	v_pk_mul_f32 v[46:47], v[46:47], v[132:133] op_sel_hi:[1,0]
	global_store_dwordx4 v[48:49], v[52:55], off
	v_add_f32_e32 v50, 1.0, v50
	v_add_f32_e32 v51, 1.0, v51
	v_exp_f32_e64 v52, -v46
	v_exp_f32_e64 v53, -v47
	v_rcp_f32_e32 v50, v50
	v_rcp_f32_e32 v51, v51
	v_add_f32_e32 v52, 1.0, v52
	v_add_f32_e32 v53, 1.0, v53
	v_rcp_f32_e32 v52, v52
	v_rcp_f32_e32 v53, v53
	v_pk_mul_f32 v[44:45], v[44:45], v[50:51]
	v_pk_mul_f32 v[36:37], v[36:37], v[132:133] op_sel_hi:[1,0]
	v_pk_mul_f32 v[38:39], v[38:39], v[132:133] op_sel_hi:[1,0]
	v_pk_mul_f32 v[36:37], v[36:37], v[44:45]
	v_pk_mul_f32 v[44:45], v[46:47], v[52:53]
	v_pk_mul_f32 v[40:41], v[40:41], v[132:133] op_sel_hi:[1,0]
	v_pk_mul_f32 v[38:39], v[38:39], v[44:45]
	v_exp_f32_e64 v46, -v40
	v_cvt_pk_bf16_f32 v36, v36, v37
	v_cvt_pk_bf16_f32 v37, v38, v39
	v_exp_f32_e64 v39, -v41
	v_pk_mul_f32 v[42:43], v[42:43], v[132:133] op_sel_hi:[1,0]
	v_add_f32_e32 v38, 1.0, v46
	v_exp_f32_e64 v44, -v42
	v_exp_f32_e64 v45, -v43
	v_add_f32_e32 v39, 1.0, v39
	v_rcp_f32_e32 v38, v38
	v_rcp_f32_e32 v39, v39
	v_add_f32_e32 v44, 1.0, v44
	v_add_f32_e32 v45, 1.0, v45
	v_rcp_f32_e32 v44, v44
	v_rcp_f32_e32 v45, v45
	v_pk_mul_f32 v[38:39], v[40:41], v[38:39]
	v_pk_mul_f32 v[32:33], v[32:33], v[132:133] op_sel_hi:[1,0]
	v_pk_mul_f32 v[34:35], v[34:35], v[132:133] op_sel_hi:[1,0]
	v_pk_mul_f32 v[32:33], v[32:33], v[38:39]
	v_pk_mul_f32 v[38:39], v[42:43], v[44:45]
	v_mad_i64_i32 v[48:49], s[0:1], v166, s52, v[124:125]
; __device__ __forceinline__ u32x2 pack4(f32x4 v) { u32x2 w; w.x = cvt_pk_bf16(v[0], v[1]); w.y = cvt_pk_bf16(v[2], v[3]); return w; }
; #define PG8_WAIT_V(n) asm volatile("s_waitcnt vmcnt(" #n ")" ::: "memory")
; #define PG8_BAR __builtin_amdgcn_s_barrier()
;     __device__ __forceinline__ void operator()(const f32x4 (&acc)[2][2][4][2], const Unit& u, int wr, int wc, int fr, int fq) const {
;     ...
;             for (int m = 0; m < 4; ++m) { const int row = row0 + ai * HALF + m * 16; bf16_t* rowp = (bf16_t*)(ws + WS_ACT) + (size_t)row * DFF + col0; u32x4e w;
; #pragma unroll
;                 for (int n = 0; n < 2; ++n) { const f32x4 a = acc[ai][0][m][n] * ri[ai][m], b = acc[ai][1][m][n] * ri[ai][m]; f32x4 o;
; #pragma unroll
;                     for (int i = 0; i < 4; ++i) o[i] = a[i] * __builtin_amdgcn_rcpf(1.0f + __builtin_amdgcn_exp2f(-a[i])) * b[i];
;                     const u32x2 p = pack4(o); w[2 * n] = p.x; w[2 * n + 1] = p.y; }
;                 *(u32x4e*)rowp = w; }
; template <class Epi, class Sched, bool ALIGN_EPI = false, bool SP2 = false>
; __device__ __forceinline__ void gemm_phase(PG8_LAS unsigned char* lds, const Gemm g, const Sched& S, const Epi& E) {
;     ...
;         if constexpr (ALIGN_EPI) { if (wr == 0) PG8_BAR; }
;         if constexpr (!Epi::AFTER_DRAIN) { E(acc, cur, wr, wc, fr, fq); S.done(cur); }
;         if (!has_next) break;
; #pragma unroll
;         for (int a = 0; a < 2; ++a)
; #pragma unroll
;             for (int b = 0; b < 2; ++b)
; #pragma unroll
;                 for (int m = 0; m < 4; ++m)
; #pragma unroll
;                     for (int n = 0; n < 2; ++n) acc[a][b][m][n] = (f32x4){0.f, 0.f, 0.f, 0.f};
;         cur = nxt; cA = nA; cB = nB; ++ui;
;         if constexpr (ALIGN_EPI) { if (wr == 1) PG8_BAR; }
;     }
;     PG8_WAIT_V(0);
;     if constexpr (!ALIGN_EPI) { if (wr == 0) PG8_BAR; }
;     PG8_BAR;
	v_pk_mul_f32 v[34:35], v[34:35], v[38:39]
	v_pk_mul_f32 v[28:29], v[28:29], v[130:131] op_sel_hi:[1,0]
	v_cvt_pk_bf16_f32 v38, v32, v33
	v_cvt_pk_bf16_f32 v39, v34, v35
	v_lshl_add_u64 v[32:33], v[48:49], 0, v[112:113]
	v_exp_f32_e64 v34, -v28
	v_exp_f32_e64 v35, -v29
	v_pk_mul_f32 v[30:31], v[30:31], v[130:131] op_sel_hi:[1,0]
	global_store_dwordx4 v[32:33], v[36:39], off
	v_add_f32_e32 v34, 1.0, v34
	v_add_f32_e32 v35, 1.0, v35
	v_exp_f32_e64 v36, -v30
	v_exp_f32_e64 v37, -v31
	v_rcp_f32_e32 v34, v34
	v_rcp_f32_e32 v35, v35
	v_add_f32_e32 v36, 1.0, v36
	v_add_f32_e32 v37, 1.0, v37
	v_rcp_f32_e32 v36, v36
	v_rcp_f32_e32 v37, v37
	v_pk_mul_f32 v[28:29], v[28:29], v[34:35]
	v_pk_mul_f32 v[20:21], v[20:21], v[130:131] op_sel_hi:[1,0]
	v_pk_mul_f32 v[22:23], v[22:23], v[130:131] op_sel_hi:[1,0]
	v_pk_mul_f32 v[20:21], v[20:21], v[28:29]
	v_pk_mul_f32 v[28:29], v[30:31], v[36:37]
	v_pk_mul_f32 v[24:25], v[24:25], v[130:131] op_sel_hi:[1,0]
	v_pk_mul_f32 v[22:23], v[22:23], v[28:29]
	v_exp_f32_e64 v30, -v24
	v_cvt_pk_bf16_f32 v20, v20, v21
	v_cvt_pk_bf16_f32 v21, v22, v23
	v_exp_f32_e64 v23, -v25
	v_pk_mul_f32 v[26:27], v[26:27], v[130:131] op_sel_hi:[1,0]
	v_add_f32_e32 v22, 1.0, v30
	v_exp_f32_e64 v28, -v26
	v_exp_f32_e64 v29, -v27
	v_add_f32_e32 v23, 1.0, v23
	v_rcp_f32_e32 v22, v22
	v_rcp_f32_e32 v23, v23
	v_add_f32_e32 v28, 1.0, v28
	v_add_f32_e32 v29, 1.0, v29
	v_rcp_f32_e32 v28, v28
	v_rcp_f32_e32 v29, v29
	v_pk_mul_f32 v[22:23], v[24:25], v[22:23]
	v_pk_mul_f32 v[16:17], v[16:17], v[130:131] op_sel_hi:[1,0]
	v_pk_mul_f32 v[18:19], v[18:19], v[130:131] op_sel_hi:[1,0]
	v_pk_mul_f32 v[16:17], v[16:17], v[22:23]
	v_pk_mul_f32 v[22:23], v[26:27], v[28:29]
	v_mad_i64_i32 v[32:33], s[0:1], v164, s52, v[124:125]
	v_pk_mul_f32 v[18:19], v[18:19], v[22:23]
	v_pk_mul_f32 v[12:13], v[12:13], v[128:129] op_sel_hi:[1,0]
	v_cvt_pk_bf16_f32 v22, v16, v17
	v_cvt_pk_bf16_f32 v23, v18, v19
	v_lshl_add_u64 v[16:17], v[32:33], 0, v[112:113]
	v_exp_f32_e64 v18, -v12
	v_exp_f32_e64 v19, -v13
	v_pk_mul_f32 v[14:15], v[14:15], v[128:129] op_sel_hi:[1,0]
	global_store_dwordx4 v[16:17], v[20:23], off
	v_add_f32_e32 v18, 1.0, v18
	v_add_f32_e32 v19, 1.0, v19
	v_exp_f32_e64 v20, -v14
	v_exp_f32_e64 v21, -v15
	v_rcp_f32_e32 v18, v18
	v_rcp_f32_e32 v19, v19
	v_add_f32_e32 v20, 1.0, v20
	v_add_f32_e32 v21, 1.0, v21
	v_rcp_f32_e32 v20, v20
	v_rcp_f32_e32 v21, v21
	v_pk_mul_f32 v[12:13], v[12:13], v[18:19]
	v_pk_mul_f32 v[4:5], v[4:5], v[128:129] op_sel_hi:[1,0]
	v_pk_mul_f32 v[6:7], v[6:7], v[128:129] op_sel_hi:[1,0]
	v_pk_mul_f32 v[4:5], v[4:5], v[12:13]
	v_pk_mul_f32 v[12:13], v[14:15], v[20:21]
	v_pk_mul_f32 v[8:9], v[8:9], v[128:129] op_sel_hi:[1,0]
	v_pk_mul_f32 v[6:7], v[6:7], v[12:13]
	v_exp_f32_e64 v14, -v8
	v_cvt_pk_bf16_f32 v4, v4, v5
	v_cvt_pk_bf16_f32 v5, v6, v7
	v_exp_f32_e64 v7, -v9
	v_pk_mul_f32 v[10:11], v[10:11], v[128:129] op_sel_hi:[1,0]
	v_add_f32_e32 v6, 1.0, v14
	v_exp_f32_e64 v12, -v10
	v_exp_f32_e64 v13, -v11
	v_add_f32_e32 v7, 1.0, v7
	v_rcp_f32_e32 v6, v6
	v_rcp_f32_e32 v7, v7
	v_add_f32_e32 v12, 1.0, v12
	v_add_f32_e32 v13, 1.0, v13
	v_rcp_f32_e32 v12, v12
	v_rcp_f32_e32 v13, v13
	v_pk_mul_f32 v[6:7], v[8:9], v[6:7]
	v_pk_mul_f32 v[0:1], v[0:1], v[128:129] op_sel_hi:[1,0]
	v_pk_mul_f32 v[2:3], v[2:3], v[128:129] op_sel_hi:[1,0]
	v_pk_mul_f32 v[0:1], v[0:1], v[6:7]
	v_pk_mul_f32 v[6:7], v[10:11], v[12:13]
	v_mad_i64_i32 v[16:17], s[0:1], v162, s52, v[124:125]
	v_pk_mul_f32 v[2:3], v[2:3], v[6:7]
	v_cvt_pk_bf16_f32 v6, v0, v1
	v_cvt_pk_bf16_f32 v7, v2, v3
	v_lshl_add_u64 v[0:1], v[16:17], 0, v[112:113]
	s_andn2_b64 vcc, exec, s[2:3]
	s_mov_b64 s[0:1], -1
	global_store_dwordx4 v[0:1], v[4:7], off
	s_cbranch_vccnz .LBB0_891
	s_andn2_b64 vcc, exec, s[6:7]
	s_cbranch_vccnz .LBB0_890
	s_branch .LBB0_890
.LBB0_901:
	s_waitcnt vmcnt(0)
	s_and_b64 vcc, exec, s[14:15]
	s_cbranch_vccz .Lna_p9
	s_barrier
.Lna_p9:
	s_barrier
.LBB0_902:
	s_waitcnt vmcnt(0)
	s_barrier
	s_mov_b64 s[0:1], exec
	v_readlane_b32 s2, v255, 1
	v_readlane_b32 s3, v255, 2
	s_and_b64 s[2:3], s[0:1], s[2:3]
	s_mov_b64 exec, s[2:3]
	s_cbranch_execz .LBB0_954
	s_add_i32 s2, 0, 0x20160
	v_mov_b32_e32 v0, s2
	s_waitcnt vmcnt(0) expcnt(0) lgkmcnt(0)
	ds_read_b32 v2, v0
	s_add_i32 s2, 0, 0x20164
	v_mov_b32_e32 v0, s2
	ds_read_b32 v0, v0
	s_waitcnt lgkmcnt(1)
	v_cmp_ne_u32_e32 vcc, 0, v2
	s_cbranch_vccnz .LBB0_918
	s_add_u32 s2, s58, 0x4200
	s_addc_u32 s3, s59, 0
	s_add_u32 s4, s58, 0x4400
	s_addc_u32 s5, s59, 0
	s_add_u32 s6, s58, 0x4500
	s_addc_u32 s7, s59, 0
	s_add_u32 s8, s58, 0x4600
	s_addc_u32 s9, s59, 0
	s_add_u32 s12, s58, 0x4700
	s_addc_u32 s13, s59, 0
	s_add_u32 s14, s58, 0x4800
	s_addc_u32 s15, s59, 0
	s_add_u32 s18, s58, 0x4900
	s_addc_u32 s19, s59, 0
	s_add_u32 s20, s58, 0x4a00
	s_addc_u32 s21, s59, 0
	s_add_u32 s22, s58, 0x4b00
	s_addc_u32 s23, s59, 0
	s_add_u32 s24, s58, 0x4c00
	s_addc_u32 s25, s59, 0
	s_add_u32 s26, s58, 0x4d00
	s_addc_u32 s27, s59, 0
	s_add_u32 s36, s58, 0x4e00
	s_addc_u32 s37, s59, 0
	s_add_u32 s38, s58, 0x4f00
	s_addc_u32 s39, s59, 0
	s_add_u32 s40, s58, 0x5000
	s_addc_u32 s41, s59, 0
	s_add_u32 s42, s58, 0x5100
	s_addc_u32 s43, s59, 0
	s_add_u32 s44, s58, 0x5200
	s_addc_u32 s45, s59, 0
	s_mul_i32 s60, s97, s11
	s_add_u32 s46, s58, 0x5300
	s_mul_i32 s60, s60, s96
	s_addc_u32 s47, s59, 0
	s_mov_b32 s61, 1
	v_mov_b32_e32 v16, 0
	s_branch .LBB0_906
